# scan step 40 -> 38.5 issue slots: y correction folded into two FMAs using a per-wave 0.25-scaled copy of the k.r / kka.r scalars kept in free LDS, read as one b128 per two steps
# speedup vs baseline: 1.0082x; 1.0062x over previous
; __device__ __forceinline__ void rwkv_item(LAS unsigned char* lds, int l, const bf16_t* PROJ, const bf16_t* LO, bf16_t* YR, float* BON, int b, int h, int qv) {
;     ...
;         __builtin_amdgcn_s_setprio(3);
;         const int rl = 8 * w + (lane >> 4), kq = lane & 15;
;         f32x2 S01[2], S23[2];
; #pragma unroll
;         for (int c = 0; c < 2; ++c) { S01[c] = (f32x2){0.f, 0.f}; S23[c] = (f32x2){0.f, 0.f}; }
;         __syncthreads();
;         for (int ci = 0; ci < NCH; ++ci) {
;             const LAS float* pk = base + (ci & 1) * BUFF + 4 * kq; const LAS float* pv = base + (ci & 1) * BUFF + 10240 + rl; const LAS float* ps = base + (ci & 1) * BUFF + 11264;
;             LAS float* py = yA + (ci & 1) * 4096 + rl * 4 + (kq >> 2);
;             f32x4 kk4 = *(const LAS f32x4*)(pk), wr4 = *(const LAS f32x4*)(pk + 2048), w4 = *(const LAS f32x4*)(pk + 4096), k4 = *(const LAS f32x4*)(pk + 6144), a4 = *(const LAS f32x4*)(pk + 8192);
;             float vv[2] = {pv[0], pv[4]}; f32x2 sc = *(const LAS f32x2*)(ps);
; #pragma unroll 32
;             for (int t = 0; t < CH; ++t) {
;                 const int tn = (t + 1) & (CH - 1);
;                 const LAS float* pn = pk + tn * 64;
;                 const f32x4 nkk = *(const LAS f32x4*)(pn), nwr = *(const LAS f32x4*)(pn + 2048), nw = *(const LAS f32x4*)(pn + 4096), nk = *(const LAS f32x4*)(pn + 6144), na = *(const LAS f32x4*)(pn + 8192);
;                 const float nv0 = pv[tn * 32], nv1 = pv[tn * 32 + 4]; const f32x2 nsc = *(const LAS f32x2*)(ps + 2 * tn);
;                 float sa[2], yp[2];
; #pragma unroll
;                 for (int c = 0; c < 2; ++c) { const f32x2 pa = S23[c] * kk4.hi + S01[c] * kk4.lo, pb = S23[c] * wr4.hi + S01[c] * wr4.lo; sa[c] = pa.x + pa.y; yp[c] = pb.x + pb.y; }
; #pragma unroll
;                 for (int c = 0; c < 2; ++c) { sa[c] = sum16(sa[c]); yp[c] += dppf<0xB1>(yp[c]); yp[c] += dppf<0x4E>(yp[c]); }
; #pragma unroll
;                 for (int c = 0; c < 2; ++c) {
;                     S01[c] = S01[c] * w4.lo + (k4.lo * vv[c] - a4.lo * sa[c]);
;                     S23[c] = S23[c] * w4.hi + (k4.hi * vv[c] - a4.hi * sa[c]);
;                     py[(t * 32 + 4 * c) * 4] = yp[c] + 0.25f * (vv[c] * sc.x - sa[c] * sc.y);
;                 }
;                 kk4 = nkk; wr4 = nwr; w4 = nw; k4 = nk; a4 = na; vv[0] = nv0; vv[1] = nv1; sc = nsc;
;             }
.LBB0_698:
	s_or_b64 exec, exec, s[30:31]
	global_load_dwordx2 v[4:5], v[4:5], off
	v_mov_b32_e32 v3, v0
	s_cmp_lt_i32 s4, 4
	s_mov_b64 s[30:31], -1
	s_waitcnt vmcnt(0)
	v_lshl_add_u64 v[2:3], v[2:3], 2, v[4:5]
	global_load_dword v2, v[2:3], off
	v_lshl_add_u32 v3, v1, 2, 0
	v_add_u32_e32 v3, 0x1e400, v3
	s_waitcnt vmcnt(0)
	ds_write_b32 v3, v2
	s_waitcnt lgkmcnt(0)
	s_barrier
	s_cbranch_scc0 .LBB0_702
	s_setprio 3
	v_and_b32_e32 v88, 15, v6
	v_lshlrev_b32_e32 v84, 4, v88
	v_lshrrev_b32_e32 v88, 4, v6
	v_lshl_or_b32 v88, s4, 3, v88
	v_and_b32_e32 v89, 3, v6
	v_lshrrev_b32_e32 v85, 1, v89
	v_xor_b32_e32 v89, v89, v85
	v_and_b32_e32 v89, 1, v89
	v_lshl_add_u32 v85, v89, 2, v88
	v_lshlrev_b32_e32 v89, 3, v89
	v_sub_u32_e32 v86, v85, v89
	v_add_u32_e32 v86, 4, v86
	v_readlane_b32 s31, v255, 7
	v_and_b32_e32 v89, 12, v6
	v_lshl_add_u32 v87, v85, 4, v89
	v_lshlrev_b32_e32 v85, 2, v85
	v_lshlrev_b32_e32 v86, 2, v86
	v_add_u32_e32 v87, s31, v87
	v_mbcnt_lo_u32_b32 v98, -1, 0
	v_mbcnt_hi_u32_b32 v98, -1, v98
	v_lshlrev_b32_e32 v98, 2, v98
	s_lshl_b32 s31, s4, 8
	s_add_i32 s31, s31, 0x1f000
	v_mov_b32_e32 v100, s31
	v_add_u32_e32 v101, s31, v98
	s_mov_b32 s30, 0
	v_mov_b32_e32 v2, 0
	v_mov_b32_e32 v3, 0
	v_mov_b32_e32 v4, 0
	v_mov_b32_e32 v5, 0
	v_mov_b32_e32 v6, 0
	v_mov_b32_e32 v7, 0
	v_mov_b32_e32 v8, 0
	v_mov_b32_e32 v9, 0
	s_barrier
.Lscan_chunk:
	s_and_b32 s24, s30, 1
	s_mul_i32 s4, s24, 0xb200
	s_lshl_b32 s31, s24, 14
	v_add_u32_e32 v10, s4, v84
	v_add_u32_e32 v11, s4, v85
	v_add_u32_e32 v12, s4, v86
	v_mov_b32_e32 v13, s4
	v_add_u32_e32 v14, s31, v87
	v_add_u32_e32 v99, s4, v98
	ds_read_b32 v102, v99 offset:45056
	ds_read_b128 v[16:19], v10 offset:0
	ds_read_b128 v[20:23], v10 offset:8192
	ds_read_b128 v[24:27], v10 offset:16384
	ds_read_b128 v[28:31], v10 offset:24576
	ds_read_b128 v[32:35], v10 offset:32768
	ds_read_b32 v36, v11 offset:40960
	ds_read_b32 v37, v12 offset:40960
	s_waitcnt lgkmcnt(7)
	v_mul_f32_e32 v102, 0x3e800000, v102
	ds_write_b32 v101, v102
	ds_read_b128 v[90:93], v100
	s_waitcnt lgkmcnt(0)
	s_waitcnt lgkmcnt(1)
	v_pk_mul_f32 v[64:65], v[2:3], v[16:17] op_sel_hi:[1,0]
	v_pk_mul_f32 v[66:67], v[2:3], v[20:21] op_sel_hi:[1,0]
	v_pk_fma_f32 v[64:65], v[4:5], v[16:17], v[64:65] op_sel:[0,1,0] op_sel_hi:[1,1,1]
	v_pk_fma_f32 v[66:67], v[4:5], v[20:21], v[66:67] op_sel:[0,1,0] op_sel_hi:[1,1,1]
	v_pk_fma_f32 v[64:65], v[6:7], v[18:19], v[64:65] op_sel_hi:[1,0,1]
	v_pk_fma_f32 v[66:67], v[6:7], v[22:23], v[66:67] op_sel_hi:[1,0,1]
	v_pk_fma_f32 v[64:65], v[8:9], v[18:19], v[64:65] op_sel:[0,1,0] op_sel_hi:[1,1,1]
	v_pk_fma_f32 v[66:67], v[8:9], v[22:23], v[66:67] op_sel:[0,1,0] op_sel_hi:[1,1,1]
	ds_read_b128 v[40:43], v10 offset:256
	v_add_f32_dpp v78, v65, v64 quad_perm:[1,0,3,2] row_mask:0xf bank_mask:0xf bound_ctrl:1
	ds_read_b128 v[44:47], v10 offset:8448
	ds_read_b128 v[48:51], v10 offset:16640
	v_add_f32_dpp v79, v78, v78 quad_perm:[3,2,1,0] row_mask:0xf bank_mask:0xf bound_ctrl:1
	ds_read_b128 v[52:55], v10 offset:24832
	ds_read_b128 v[56:59], v10 offset:33024
	v_add_f32_dpp v80, v79, v79 row_half_mirror row_mask:0xf bank_mask:0xf bound_ctrl:1
	ds_read_b32 v60, v11 offset:41088
	ds_read_b32 v61, v12 offset:41088
	v_add_f32_dpp v76, v80, v80 row_mirror row_mask:0xf bank_mask:0xf bound_ctrl:1
	ds_read_b128 v[94:97], v100 offset:16
	v_pk_mul_f32 v[68:69], v[36:37], v[28:29] op_sel_hi:[1,0]
	v_pk_mul_f32 v[70:71], v[36:37], v[28:29] op_sel:[0,1] op_sel_hi:[1,1]
	v_mov_b32_dpp v77, v76 quad_perm:[1,0,3,2] row_mask:0xf bank_mask:0xf bound_ctrl:1
	v_pk_mul_f32 v[72:73], v[36:37], v[30:31] op_sel_hi:[1,0]
	v_pk_mul_f32 v[74:75], v[36:37], v[30:31] op_sel:[0,1] op_sel_hi:[1,1]
	v_pk_fma_f32 v[68:69], v[2:3], v[24:25], v[68:69] op_sel_hi:[1,0,1]
	v_pk_fma_f32 v[70:71], v[4:5], v[24:25], v[70:71] op_sel:[0,1,0] op_sel_hi:[1,1,1]
	v_pk_fma_f32 v[72:73], v[6:7], v[26:27], v[72:73] op_sel_hi:[1,0,1]
	v_pk_fma_f32 v[74:75], v[8:9], v[26:27], v[74:75] op_sel:[0,1,0] op_sel_hi:[1,1,1]
	v_pk_fma_f32 v[2:3], v[32:33], v[76:77], v[68:69] op_sel_hi:[0,1,1] neg_lo:[1,0,0] neg_hi:[1,0,0]
	v_pk_fma_f32 v[4:5], v[32:33], v[76:77], v[70:71] op_sel:[1,0,0] op_sel_hi:[1,1,1] neg_lo:[1,0,0] neg_hi:[1,0,0]
	v_add_f32_dpp v81, v67, v66 quad_perm:[1,0,3,2] row_mask:0xf bank_mask:0xf bound_ctrl:1
	v_pk_fma_f32 v[6:7], v[34:35], v[76:77], v[72:73] op_sel_hi:[0,1,1] neg_lo:[1,0,0] neg_hi:[1,0,0]
	v_pk_fma_f32 v[8:9], v[34:35], v[76:77], v[74:75] op_sel:[1,0,0] op_sel_hi:[1,1,1] neg_lo:[1,0,0] neg_hi:[1,0,0]
	v_add_f32_dpp v82, v81, v81 quad_perm:[3,2,1,0] row_mask:0xf bank_mask:0xf bound_ctrl:1
	v_fma_f32 v83, v36, v90, v82
	v_fma_f32 v82, -v76, v91, v83
	ds_write_b32 v14, v82 offset:0
	s_waitcnt lgkmcnt(1)
; #define LAS __attribute__((address_space(3)))
; template <int CTRL> __device__ __forceinline__ float dppf(float x) { return __builtin_bit_cast(float, __builtin_amdgcn_mov_dpp(__builtin_bit_cast(int, x), CTRL, 0xf, 0xf, true)); }
; __device__ __forceinline__ float sum16(float x) { x = sum8(x); x += dppf<0x140>(x); return x; }
; __device__ __forceinline__ void rwkv_item(LAS unsigned char* lds, int l, const bf16_t* PROJ, const bf16_t* LO, bf16_t* YR, float* BON, int b, int h, int qv) {
;     ...
;             for (int t = 0; t < CH; ++t) {
;                 const int tn = (t + 1) & (CH - 1);
;                 const LAS float* pn = pk + tn * 64;
;                 const f32x4 nkk = *(const LAS f32x4*)(pn), nwr = *(const LAS f32x4*)(pn + 2048), nw = *(const LAS f32x4*)(pn + 4096), nk = *(const LAS f32x4*)(pn + 6144), na = *(const LAS f32x4*)(pn + 8192);
;                 const float nv0 = pv[tn * 32], nv1 = pv[tn * 32 + 4]; const f32x2 nsc = *(const LAS f32x2*)(ps + 2 * tn);
;                 float sa[2], yp[2];
; #pragma unroll
;                 for (int c = 0; c < 2; ++c) { const f32x2 pa = S23[c] * kk4.hi + S01[c] * kk4.lo, pb = S23[c] * wr4.hi + S01[c] * wr4.lo; sa[c] = pa.x + pa.y; yp[c] = pb.x + pb.y; }
; #pragma unroll
;                 for (int c = 0; c < 2; ++c) { sa[c] = sum16(sa[c]); yp[c] += dppf<0xB1>(yp[c]); yp[c] += dppf<0x4E>(yp[c]); }
; #pragma unroll
;                 for (int c = 0; c < 2; ++c) {
;                     S01[c] = S01[c] * w4.lo + (k4.lo * vv[c] - a4.lo * sa[c]);
;                     S23[c] = S23[c] * w4.hi + (k4.hi * vv[c] - a4.hi * sa[c]);
;                     py[(t * 32 + 4 * c) * 4] = yp[c] + 0.25f * (vv[c] * sc.x - sa[c] * sc.y);
;                 }
;                 kk4 = nkk; wr4 = nwr; w4 = nw; k4 = nk; a4 = na; vv[0] = nv0; vv[1] = nv1; sc = nsc;
;             }
	v_pk_mul_f32 v[64:65], v[2:3], v[40:41] op_sel_hi:[1,0]
	v_pk_mul_f32 v[66:67], v[2:3], v[44:45] op_sel_hi:[1,0]
	v_pk_fma_f32 v[64:65], v[4:5], v[40:41], v[64:65] op_sel:[0,1,0] op_sel_hi:[1,1,1]
	v_pk_fma_f32 v[66:67], v[4:5], v[44:45], v[66:67] op_sel:[0,1,0] op_sel_hi:[1,1,1]
	v_pk_fma_f32 v[64:65], v[6:7], v[42:43], v[64:65] op_sel_hi:[1,0,1]
	v_pk_fma_f32 v[66:67], v[6:7], v[46:47], v[66:67] op_sel_hi:[1,0,1]
	v_pk_fma_f32 v[64:65], v[8:9], v[42:43], v[64:65] op_sel:[0,1,0] op_sel_hi:[1,1,1]
	v_pk_fma_f32 v[66:67], v[8:9], v[46:47], v[66:67] op_sel:[0,1,0] op_sel_hi:[1,1,1]
	ds_read_b128 v[16:19], v10 offset:512
	v_add_f32_dpp v78, v65, v64 quad_perm:[1,0,3,2] row_mask:0xf bank_mask:0xf bound_ctrl:1
	ds_read_b128 v[20:23], v10 offset:8704
	ds_read_b128 v[24:27], v10 offset:16896
	v_add_f32_dpp v79, v78, v78 quad_perm:[3,2,1,0] row_mask:0xf bank_mask:0xf bound_ctrl:1
	ds_read_b128 v[28:31], v10 offset:25088
	ds_read_b128 v[32:35], v10 offset:33280
	v_add_f32_dpp v80, v79, v79 row_half_mirror row_mask:0xf bank_mask:0xf bound_ctrl:1
	ds_read_b32 v36, v11 offset:41216
	ds_read_b32 v37, v12 offset:41216
	v_add_f32_dpp v76, v80, v80 row_mirror row_mask:0xf bank_mask:0xf bound_ctrl:1
	v_pk_mul_f32 v[68:69], v[60:61], v[52:53] op_sel_hi:[1,0]
	v_pk_mul_f32 v[70:71], v[60:61], v[52:53] op_sel:[0,1] op_sel_hi:[1,1]
	v_mov_b32_dpp v77, v76 quad_perm:[1,0,3,2] row_mask:0xf bank_mask:0xf bound_ctrl:1
	v_pk_mul_f32 v[72:73], v[60:61], v[54:55] op_sel_hi:[1,0]
	v_pk_mul_f32 v[74:75], v[60:61], v[54:55] op_sel:[0,1] op_sel_hi:[1,1]
	v_pk_fma_f32 v[68:69], v[2:3], v[48:49], v[68:69] op_sel_hi:[1,0,1]
	v_pk_fma_f32 v[70:71], v[4:5], v[48:49], v[70:71] op_sel:[0,1,0] op_sel_hi:[1,1,1]
	v_pk_fma_f32 v[72:73], v[6:7], v[50:51], v[72:73] op_sel_hi:[1,0,1]
	v_pk_fma_f32 v[74:75], v[8:9], v[50:51], v[74:75] op_sel:[0,1,0] op_sel_hi:[1,1,1]
	v_pk_fma_f32 v[2:3], v[56:57], v[76:77], v[68:69] op_sel_hi:[0,1,1] neg_lo:[1,0,0] neg_hi:[1,0,0]
	v_pk_fma_f32 v[4:5], v[56:57], v[76:77], v[70:71] op_sel:[1,0,0] op_sel_hi:[1,1,1] neg_lo:[1,0,0] neg_hi:[1,0,0]
	v_add_f32_dpp v81, v67, v66 quad_perm:[1,0,3,2] row_mask:0xf bank_mask:0xf bound_ctrl:1
	v_pk_fma_f32 v[6:7], v[58:59], v[76:77], v[72:73] op_sel_hi:[0,1,1] neg_lo:[1,0,0] neg_hi:[1,0,0]
	v_pk_fma_f32 v[8:9], v[58:59], v[76:77], v[74:75] op_sel:[1,0,0] op_sel_hi:[1,1,1] neg_lo:[1,0,0] neg_hi:[1,0,0]
	v_add_f32_dpp v82, v81, v81 quad_perm:[3,2,1,0] row_mask:0xf bank_mask:0xf bound_ctrl:1
	v_fma_f32 v83, v60, v92, v82
	v_fma_f32 v82, -v76, v93, v83
	ds_write_b32 v14, v82 offset:512
	s_waitcnt lgkmcnt(1)
	v_pk_mul_f32 v[64:65], v[2:3], v[16:17] op_sel_hi:[1,0]
	v_pk_mul_f32 v[66:67], v[2:3], v[20:21] op_sel_hi:[1,0]
	v_pk_fma_f32 v[64:65], v[4:5], v[16:17], v[64:65] op_sel:[0,1,0] op_sel_hi:[1,1,1]
	v_pk_fma_f32 v[66:67], v[4:5], v[20:21], v[66:67] op_sel:[0,1,0] op_sel_hi:[1,1,1]
	v_pk_fma_f32 v[64:65], v[6:7], v[18:19], v[64:65] op_sel_hi:[1,0,1]
	v_pk_fma_f32 v[66:67], v[6:7], v[22:23], v[66:67] op_sel_hi:[1,0,1]
	v_pk_fma_f32 v[64:65], v[8:9], v[18:19], v[64:65] op_sel:[0,1,0] op_sel_hi:[1,1,1]
	v_pk_fma_f32 v[66:67], v[8:9], v[22:23], v[66:67] op_sel:[0,1,0] op_sel_hi:[1,1,1]
	ds_read_b128 v[40:43], v10 offset:768
	v_add_f32_dpp v78, v65, v64 quad_perm:[1,0,3,2] row_mask:0xf bank_mask:0xf bound_ctrl:1
	ds_read_b128 v[44:47], v10 offset:8960
	ds_read_b128 v[48:51], v10 offset:17152
	v_add_f32_dpp v79, v78, v78 quad_perm:[3,2,1,0] row_mask:0xf bank_mask:0xf bound_ctrl:1
	ds_read_b128 v[52:55], v10 offset:25344
	ds_read_b128 v[56:59], v10 offset:33536
	v_add_f32_dpp v80, v79, v79 row_half_mirror row_mask:0xf bank_mask:0xf bound_ctrl:1
	ds_read_b32 v60, v11 offset:41344
	ds_read_b32 v61, v12 offset:41344
	v_add_f32_dpp v76, v80, v80 row_mirror row_mask:0xf bank_mask:0xf bound_ctrl:1
	ds_read_b128 v[90:93], v100 offset:32
	v_pk_mul_f32 v[68:69], v[36:37], v[28:29] op_sel_hi:[1,0]
	v_pk_mul_f32 v[70:71], v[36:37], v[28:29] op_sel:[0,1] op_sel_hi:[1,1]
	v_mov_b32_dpp v77, v76 quad_perm:[1,0,3,2] row_mask:0xf bank_mask:0xf bound_ctrl:1
	v_pk_mul_f32 v[72:73], v[36:37], v[30:31] op_sel_hi:[1,0]
	v_pk_mul_f32 v[74:75], v[36:37], v[30:31] op_sel:[0,1] op_sel_hi:[1,1]
	v_pk_fma_f32 v[68:69], v[2:3], v[24:25], v[68:69] op_sel_hi:[1,0,1]
	v_pk_fma_f32 v[70:71], v[4:5], v[24:25], v[70:71] op_sel:[0,1,0] op_sel_hi:[1,1,1]
	v_pk_fma_f32 v[72:73], v[6:7], v[26:27], v[72:73] op_sel_hi:[1,0,1]
	v_pk_fma_f32 v[74:75], v[8:9], v[26:27], v[74:75] op_sel:[0,1,0] op_sel_hi:[1,1,1]
	v_pk_fma_f32 v[2:3], v[32:33], v[76:77], v[68:69] op_sel_hi:[0,1,1] neg_lo:[1,0,0] neg_hi:[1,0,0]
	v_pk_fma_f32 v[4:5], v[32:33], v[76:77], v[70:71] op_sel:[1,0,0] op_sel_hi:[1,1,1] neg_lo:[1,0,0] neg_hi:[1,0,0]
	v_add_f32_dpp v81, v67, v66 quad_perm:[1,0,3,2] row_mask:0xf bank_mask:0xf bound_ctrl:1
	v_pk_fma_f32 v[6:7], v[34:35], v[76:77], v[72:73] op_sel_hi:[0,1,1] neg_lo:[1,0,0] neg_hi:[1,0,0]
	v_pk_fma_f32 v[8:9], v[34:35], v[76:77], v[74:75] op_sel:[1,0,0] op_sel_hi:[1,1,1] neg_lo:[1,0,0] neg_hi:[1,0,0]
	v_add_f32_dpp v82, v81, v81 quad_perm:[3,2,1,0] row_mask:0xf bank_mask:0xf bound_ctrl:1
	v_fma_f32 v83, v36, v94, v82
	v_fma_f32 v82, -v76, v95, v83
	ds_write_b32 v14, v82 offset:1024
	s_waitcnt lgkmcnt(1)
; #define LAS __attribute__((address_space(3)))
; template <int CTRL> __device__ __forceinline__ float dppf(float x) { return __builtin_bit_cast(float, __builtin_amdgcn_mov_dpp(__builtin_bit_cast(int, x), CTRL, 0xf, 0xf, true)); }
; __device__ __forceinline__ float sum16(float x) { x = sum8(x); x += dppf<0x140>(x); return x; }
; __device__ __forceinline__ void rwkv_item(LAS unsigned char* lds, int l, const bf16_t* PROJ, const bf16_t* LO, bf16_t* YR, float* BON, int b, int h, int qv) {
;     ...
;             for (int t = 0; t < CH; ++t) {
;                 const int tn = (t + 1) & (CH - 1);
;                 const LAS float* pn = pk + tn * 64;
;                 const f32x4 nkk = *(const LAS f32x4*)(pn), nwr = *(const LAS f32x4*)(pn + 2048), nw = *(const LAS f32x4*)(pn + 4096), nk = *(const LAS f32x4*)(pn + 6144), na = *(const LAS f32x4*)(pn + 8192);
;                 const float nv0 = pv[tn * 32], nv1 = pv[tn * 32 + 4]; const f32x2 nsc = *(const LAS f32x2*)(ps + 2 * tn);
;                 float sa[2], yp[2];
; #pragma unroll
;                 for (int c = 0; c < 2; ++c) { const f32x2 pa = S23[c] * kk4.hi + S01[c] * kk4.lo, pb = S23[c] * wr4.hi + S01[c] * wr4.lo; sa[c] = pa.x + pa.y; yp[c] = pb.x + pb.y; }
; #pragma unroll
;                 for (int c = 0; c < 2; ++c) { sa[c] = sum16(sa[c]); yp[c] += dppf<0xB1>(yp[c]); yp[c] += dppf<0x4E>(yp[c]); }
; #pragma unroll
;                 for (int c = 0; c < 2; ++c) {
;                     S01[c] = S01[c] * w4.lo + (k4.lo * vv[c] - a4.lo * sa[c]);
;                     S23[c] = S23[c] * w4.hi + (k4.hi * vv[c] - a4.hi * sa[c]);
;                     py[(t * 32 + 4 * c) * 4] = yp[c] + 0.25f * (vv[c] * sc.x - sa[c] * sc.y);
;                 }
;                 kk4 = nkk; wr4 = nwr; w4 = nw; k4 = nk; a4 = na; vv[0] = nv0; vv[1] = nv1; sc = nsc;
;             }
	v_pk_mul_f32 v[64:65], v[2:3], v[40:41] op_sel_hi:[1,0]
	v_pk_mul_f32 v[66:67], v[2:3], v[44:45] op_sel_hi:[1,0]
	v_pk_fma_f32 v[64:65], v[4:5], v[40:41], v[64:65] op_sel:[0,1,0] op_sel_hi:[1,1,1]
	v_pk_fma_f32 v[66:67], v[4:5], v[44:45], v[66:67] op_sel:[0,1,0] op_sel_hi:[1,1,1]
	v_pk_fma_f32 v[64:65], v[6:7], v[42:43], v[64:65] op_sel_hi:[1,0,1]
	v_pk_fma_f32 v[66:67], v[6:7], v[46:47], v[66:67] op_sel_hi:[1,0,1]
	v_pk_fma_f32 v[64:65], v[8:9], v[42:43], v[64:65] op_sel:[0,1,0] op_sel_hi:[1,1,1]
	v_pk_fma_f32 v[66:67], v[8:9], v[46:47], v[66:67] op_sel:[0,1,0] op_sel_hi:[1,1,1]
	ds_read_b128 v[16:19], v10 offset:1024
	v_add_f32_dpp v78, v65, v64 quad_perm:[1,0,3,2] row_mask:0xf bank_mask:0xf bound_ctrl:1
	ds_read_b128 v[20:23], v10 offset:9216
	ds_read_b128 v[24:27], v10 offset:17408
	v_add_f32_dpp v79, v78, v78 quad_perm:[3,2,1,0] row_mask:0xf bank_mask:0xf bound_ctrl:1
	ds_read_b128 v[28:31], v10 offset:25600
	ds_read_b128 v[32:35], v10 offset:33792
	v_add_f32_dpp v80, v79, v79 row_half_mirror row_mask:0xf bank_mask:0xf bound_ctrl:1
	ds_read_b32 v36, v11 offset:41472
	ds_read_b32 v37, v12 offset:41472
	v_add_f32_dpp v76, v80, v80 row_mirror row_mask:0xf bank_mask:0xf bound_ctrl:1
	v_pk_mul_f32 v[68:69], v[60:61], v[52:53] op_sel_hi:[1,0]
	v_pk_mul_f32 v[70:71], v[60:61], v[52:53] op_sel:[0,1] op_sel_hi:[1,1]
	v_mov_b32_dpp v77, v76 quad_perm:[1,0,3,2] row_mask:0xf bank_mask:0xf bound_ctrl:1
	v_pk_mul_f32 v[72:73], v[60:61], v[54:55] op_sel_hi:[1,0]
	v_pk_mul_f32 v[74:75], v[60:61], v[54:55] op_sel:[0,1] op_sel_hi:[1,1]
	v_pk_fma_f32 v[68:69], v[2:3], v[48:49], v[68:69] op_sel_hi:[1,0,1]
	v_pk_fma_f32 v[70:71], v[4:5], v[48:49], v[70:71] op_sel:[0,1,0] op_sel_hi:[1,1,1]
	v_pk_fma_f32 v[72:73], v[6:7], v[50:51], v[72:73] op_sel_hi:[1,0,1]
	v_pk_fma_f32 v[74:75], v[8:9], v[50:51], v[74:75] op_sel:[0,1,0] op_sel_hi:[1,1,1]
	v_pk_fma_f32 v[2:3], v[56:57], v[76:77], v[68:69] op_sel_hi:[0,1,1] neg_lo:[1,0,0] neg_hi:[1,0,0]
	v_pk_fma_f32 v[4:5], v[56:57], v[76:77], v[70:71] op_sel:[1,0,0] op_sel_hi:[1,1,1] neg_lo:[1,0,0] neg_hi:[1,0,0]
	v_add_f32_dpp v81, v67, v66 quad_perm:[1,0,3,2] row_mask:0xf bank_mask:0xf bound_ctrl:1
	v_pk_fma_f32 v[6:7], v[58:59], v[76:77], v[72:73] op_sel_hi:[0,1,1] neg_lo:[1,0,0] neg_hi:[1,0,0]
	v_pk_fma_f32 v[8:9], v[58:59], v[76:77], v[74:75] op_sel:[1,0,0] op_sel_hi:[1,1,1] neg_lo:[1,0,0] neg_hi:[1,0,0]
	v_add_f32_dpp v82, v81, v81 quad_perm:[3,2,1,0] row_mask:0xf bank_mask:0xf bound_ctrl:1
	v_fma_f32 v83, v60, v96, v82
	v_fma_f32 v82, -v76, v97, v83
	ds_write_b32 v14, v82 offset:1536
	s_waitcnt lgkmcnt(1)
	v_pk_mul_f32 v[64:65], v[2:3], v[16:17] op_sel_hi:[1,0]
	v_pk_mul_f32 v[66:67], v[2:3], v[20:21] op_sel_hi:[1,0]
	v_pk_fma_f32 v[64:65], v[4:5], v[16:17], v[64:65] op_sel:[0,1,0] op_sel_hi:[1,1,1]
	v_pk_fma_f32 v[66:67], v[4:5], v[20:21], v[66:67] op_sel:[0,1,0] op_sel_hi:[1,1,1]
	v_pk_fma_f32 v[64:65], v[6:7], v[18:19], v[64:65] op_sel_hi:[1,0,1]
	v_pk_fma_f32 v[66:67], v[6:7], v[22:23], v[66:67] op_sel_hi:[1,0,1]
	v_pk_fma_f32 v[64:65], v[8:9], v[18:19], v[64:65] op_sel:[0,1,0] op_sel_hi:[1,1,1]
	v_pk_fma_f32 v[66:67], v[8:9], v[22:23], v[66:67] op_sel:[0,1,0] op_sel_hi:[1,1,1]
	ds_read_b128 v[40:43], v10 offset:1280
	v_add_f32_dpp v78, v65, v64 quad_perm:[1,0,3,2] row_mask:0xf bank_mask:0xf bound_ctrl:1
	ds_read_b128 v[44:47], v10 offset:9472
	ds_read_b128 v[48:51], v10 offset:17664
	v_add_f32_dpp v79, v78, v78 quad_perm:[3,2,1,0] row_mask:0xf bank_mask:0xf bound_ctrl:1
	ds_read_b128 v[52:55], v10 offset:25856
	ds_read_b128 v[56:59], v10 offset:34048
	v_add_f32_dpp v80, v79, v79 row_half_mirror row_mask:0xf bank_mask:0xf bound_ctrl:1
	ds_read_b32 v60, v11 offset:41600
	ds_read_b32 v61, v12 offset:41600
	v_add_f32_dpp v76, v80, v80 row_mirror row_mask:0xf bank_mask:0xf bound_ctrl:1
	ds_read_b128 v[94:97], v100 offset:48
	v_pk_mul_f32 v[68:69], v[36:37], v[28:29] op_sel_hi:[1,0]
	v_pk_mul_f32 v[70:71], v[36:37], v[28:29] op_sel:[0,1] op_sel_hi:[1,1]
	v_mov_b32_dpp v77, v76 quad_perm:[1,0,3,2] row_mask:0xf bank_mask:0xf bound_ctrl:1
	v_pk_mul_f32 v[72:73], v[36:37], v[30:31] op_sel_hi:[1,0]
	v_pk_mul_f32 v[74:75], v[36:37], v[30:31] op_sel:[0,1] op_sel_hi:[1,1]
	v_pk_fma_f32 v[68:69], v[2:3], v[24:25], v[68:69] op_sel_hi:[1,0,1]
	v_pk_fma_f32 v[70:71], v[4:5], v[24:25], v[70:71] op_sel:[0,1,0] op_sel_hi:[1,1,1]
	v_pk_fma_f32 v[72:73], v[6:7], v[26:27], v[72:73] op_sel_hi:[1,0,1]
	v_pk_fma_f32 v[74:75], v[8:9], v[26:27], v[74:75] op_sel:[0,1,0] op_sel_hi:[1,1,1]
	v_pk_fma_f32 v[2:3], v[32:33], v[76:77], v[68:69] op_sel_hi:[0,1,1] neg_lo:[1,0,0] neg_hi:[1,0,0]
	v_pk_fma_f32 v[4:5], v[32:33], v[76:77], v[70:71] op_sel:[1,0,0] op_sel_hi:[1,1,1] neg_lo:[1,0,0] neg_hi:[1,0,0]
	v_add_f32_dpp v81, v67, v66 quad_perm:[1,0,3,2] row_mask:0xf bank_mask:0xf bound_ctrl:1
	v_pk_fma_f32 v[6:7], v[34:35], v[76:77], v[72:73] op_sel_hi:[0,1,1] neg_lo:[1,0,0] neg_hi:[1,0,0]
	v_pk_fma_f32 v[8:9], v[34:35], v[76:77], v[74:75] op_sel:[1,0,0] op_sel_hi:[1,1,1] neg_lo:[1,0,0] neg_hi:[1,0,0]
	v_add_f32_dpp v82, v81, v81 quad_perm:[3,2,1,0] row_mask:0xf bank_mask:0xf bound_ctrl:1
	v_fma_f32 v83, v36, v90, v82
	v_fma_f32 v82, -v76, v91, v83
	ds_write_b32 v14, v82 offset:2048
	s_waitcnt lgkmcnt(1)
; #define LAS __attribute__((address_space(3)))
; template <int CTRL> __device__ __forceinline__ float dppf(float x) { return __builtin_bit_cast(float, __builtin_amdgcn_mov_dpp(__builtin_bit_cast(int, x), CTRL, 0xf, 0xf, true)); }
; __device__ __forceinline__ float sum16(float x) { x = sum8(x); x += dppf<0x140>(x); return x; }
; __device__ __forceinline__ void rwkv_item(LAS unsigned char* lds, int l, const bf16_t* PROJ, const bf16_t* LO, bf16_t* YR, float* BON, int b, int h, int qv) {
;     ...
;             for (int t = 0; t < CH; ++t) {
;                 const int tn = (t + 1) & (CH - 1);
;                 const LAS float* pn = pk + tn * 64;
;                 const f32x4 nkk = *(const LAS f32x4*)(pn), nwr = *(const LAS f32x4*)(pn + 2048), nw = *(const LAS f32x4*)(pn + 4096), nk = *(const LAS f32x4*)(pn + 6144), na = *(const LAS f32x4*)(pn + 8192);
;                 const float nv0 = pv[tn * 32], nv1 = pv[tn * 32 + 4]; const f32x2 nsc = *(const LAS f32x2*)(ps + 2 * tn);
;                 float sa[2], yp[2];
; #pragma unroll
;                 for (int c = 0; c < 2; ++c) { const f32x2 pa = S23[c] * kk4.hi + S01[c] * kk4.lo, pb = S23[c] * wr4.hi + S01[c] * wr4.lo; sa[c] = pa.x + pa.y; yp[c] = pb.x + pb.y; }
; #pragma unroll
;                 for (int c = 0; c < 2; ++c) { sa[c] = sum16(sa[c]); yp[c] += dppf<0xB1>(yp[c]); yp[c] += dppf<0x4E>(yp[c]); }
; #pragma unroll
;                 for (int c = 0; c < 2; ++c) {
;                     S01[c] = S01[c] * w4.lo + (k4.lo * vv[c] - a4.lo * sa[c]);
;                     S23[c] = S23[c] * w4.hi + (k4.hi * vv[c] - a4.hi * sa[c]);
;                     py[(t * 32 + 4 * c) * 4] = yp[c] + 0.25f * (vv[c] * sc.x - sa[c] * sc.y);
;                 }
;                 kk4 = nkk; wr4 = nwr; w4 = nw; k4 = nk; a4 = na; vv[0] = nv0; vv[1] = nv1; sc = nsc;
;             }
	v_pk_mul_f32 v[64:65], v[2:3], v[40:41] op_sel_hi:[1,0]
	v_pk_mul_f32 v[66:67], v[2:3], v[44:45] op_sel_hi:[1,0]
	v_pk_fma_f32 v[64:65], v[4:5], v[40:41], v[64:65] op_sel:[0,1,0] op_sel_hi:[1,1,1]
	v_pk_fma_f32 v[66:67], v[4:5], v[44:45], v[66:67] op_sel:[0,1,0] op_sel_hi:[1,1,1]
	v_pk_fma_f32 v[64:65], v[6:7], v[42:43], v[64:65] op_sel_hi:[1,0,1]
	v_pk_fma_f32 v[66:67], v[6:7], v[46:47], v[66:67] op_sel_hi:[1,0,1]
	v_pk_fma_f32 v[64:65], v[8:9], v[42:43], v[64:65] op_sel:[0,1,0] op_sel_hi:[1,1,1]
	v_pk_fma_f32 v[66:67], v[8:9], v[46:47], v[66:67] op_sel:[0,1,0] op_sel_hi:[1,1,1]
	ds_read_b128 v[16:19], v10 offset:1536
	v_add_f32_dpp v78, v65, v64 quad_perm:[1,0,3,2] row_mask:0xf bank_mask:0xf bound_ctrl:1
	ds_read_b128 v[20:23], v10 offset:9728
	ds_read_b128 v[24:27], v10 offset:17920
	v_add_f32_dpp v79, v78, v78 quad_perm:[3,2,1,0] row_mask:0xf bank_mask:0xf bound_ctrl:1
	ds_read_b128 v[28:31], v10 offset:26112
	ds_read_b128 v[32:35], v10 offset:34304
	v_add_f32_dpp v80, v79, v79 row_half_mirror row_mask:0xf bank_mask:0xf bound_ctrl:1
	ds_read_b32 v36, v11 offset:41728
	ds_read_b32 v37, v12 offset:41728
	v_add_f32_dpp v76, v80, v80 row_mirror row_mask:0xf bank_mask:0xf bound_ctrl:1
	v_pk_mul_f32 v[68:69], v[60:61], v[52:53] op_sel_hi:[1,0]
	v_pk_mul_f32 v[70:71], v[60:61], v[52:53] op_sel:[0,1] op_sel_hi:[1,1]
	v_mov_b32_dpp v77, v76 quad_perm:[1,0,3,2] row_mask:0xf bank_mask:0xf bound_ctrl:1
	v_pk_mul_f32 v[72:73], v[60:61], v[54:55] op_sel_hi:[1,0]
	v_pk_mul_f32 v[74:75], v[60:61], v[54:55] op_sel:[0,1] op_sel_hi:[1,1]
	v_pk_fma_f32 v[68:69], v[2:3], v[48:49], v[68:69] op_sel_hi:[1,0,1]
	v_pk_fma_f32 v[70:71], v[4:5], v[48:49], v[70:71] op_sel:[0,1,0] op_sel_hi:[1,1,1]
	v_pk_fma_f32 v[72:73], v[6:7], v[50:51], v[72:73] op_sel_hi:[1,0,1]
	v_pk_fma_f32 v[74:75], v[8:9], v[50:51], v[74:75] op_sel:[0,1,0] op_sel_hi:[1,1,1]
	v_pk_fma_f32 v[2:3], v[56:57], v[76:77], v[68:69] op_sel_hi:[0,1,1] neg_lo:[1,0,0] neg_hi:[1,0,0]
	v_pk_fma_f32 v[4:5], v[56:57], v[76:77], v[70:71] op_sel:[1,0,0] op_sel_hi:[1,1,1] neg_lo:[1,0,0] neg_hi:[1,0,0]
	v_add_f32_dpp v81, v67, v66 quad_perm:[1,0,3,2] row_mask:0xf bank_mask:0xf bound_ctrl:1
	v_pk_fma_f32 v[6:7], v[58:59], v[76:77], v[72:73] op_sel_hi:[0,1,1] neg_lo:[1,0,0] neg_hi:[1,0,0]
	v_pk_fma_f32 v[8:9], v[58:59], v[76:77], v[74:75] op_sel:[1,0,0] op_sel_hi:[1,1,1] neg_lo:[1,0,0] neg_hi:[1,0,0]
	v_add_f32_dpp v82, v81, v81 quad_perm:[3,2,1,0] row_mask:0xf bank_mask:0xf bound_ctrl:1
	v_fma_f32 v83, v60, v92, v82
	v_fma_f32 v82, -v76, v93, v83
	ds_write_b32 v14, v82 offset:2560
	s_waitcnt lgkmcnt(1)
	v_pk_mul_f32 v[64:65], v[2:3], v[16:17] op_sel_hi:[1,0]
	v_pk_mul_f32 v[66:67], v[2:3], v[20:21] op_sel_hi:[1,0]
	v_pk_fma_f32 v[64:65], v[4:5], v[16:17], v[64:65] op_sel:[0,1,0] op_sel_hi:[1,1,1]
	v_pk_fma_f32 v[66:67], v[4:5], v[20:21], v[66:67] op_sel:[0,1,0] op_sel_hi:[1,1,1]
	v_pk_fma_f32 v[64:65], v[6:7], v[18:19], v[64:65] op_sel_hi:[1,0,1]
	v_pk_fma_f32 v[66:67], v[6:7], v[22:23], v[66:67] op_sel_hi:[1,0,1]
	v_pk_fma_f32 v[64:65], v[8:9], v[18:19], v[64:65] op_sel:[0,1,0] op_sel_hi:[1,1,1]
	v_pk_fma_f32 v[66:67], v[8:9], v[22:23], v[66:67] op_sel:[0,1,0] op_sel_hi:[1,1,1]
	ds_read_b128 v[40:43], v10 offset:1792
	v_add_f32_dpp v78, v65, v64 quad_perm:[1,0,3,2] row_mask:0xf bank_mask:0xf bound_ctrl:1
	ds_read_b128 v[44:47], v10 offset:9984
	ds_read_b128 v[48:51], v10 offset:18176
	v_add_f32_dpp v79, v78, v78 quad_perm:[3,2,1,0] row_mask:0xf bank_mask:0xf bound_ctrl:1
	ds_read_b128 v[52:55], v10 offset:26368
	ds_read_b128 v[56:59], v10 offset:34560
	v_add_f32_dpp v80, v79, v79 row_half_mirror row_mask:0xf bank_mask:0xf bound_ctrl:1
	ds_read_b32 v60, v11 offset:41856
	ds_read_b32 v61, v12 offset:41856
	v_add_f32_dpp v76, v80, v80 row_mirror row_mask:0xf bank_mask:0xf bound_ctrl:1
	ds_read_b128 v[90:93], v100 offset:64
	v_pk_mul_f32 v[68:69], v[36:37], v[28:29] op_sel_hi:[1,0]
	v_pk_mul_f32 v[70:71], v[36:37], v[28:29] op_sel:[0,1] op_sel_hi:[1,1]
	v_mov_b32_dpp v77, v76 quad_perm:[1,0,3,2] row_mask:0xf bank_mask:0xf bound_ctrl:1
	v_pk_mul_f32 v[72:73], v[36:37], v[30:31] op_sel_hi:[1,0]
	v_pk_mul_f32 v[74:75], v[36:37], v[30:31] op_sel:[0,1] op_sel_hi:[1,1]
	v_pk_fma_f32 v[68:69], v[2:3], v[24:25], v[68:69] op_sel_hi:[1,0,1]
	v_pk_fma_f32 v[70:71], v[4:5], v[24:25], v[70:71] op_sel:[0,1,0] op_sel_hi:[1,1,1]
	v_pk_fma_f32 v[72:73], v[6:7], v[26:27], v[72:73] op_sel_hi:[1,0,1]
	v_pk_fma_f32 v[74:75], v[8:9], v[26:27], v[74:75] op_sel:[0,1,0] op_sel_hi:[1,1,1]
	v_pk_fma_f32 v[2:3], v[32:33], v[76:77], v[68:69] op_sel_hi:[0,1,1] neg_lo:[1,0,0] neg_hi:[1,0,0]
	v_pk_fma_f32 v[4:5], v[32:33], v[76:77], v[70:71] op_sel:[1,0,0] op_sel_hi:[1,1,1] neg_lo:[1,0,0] neg_hi:[1,0,0]
	v_add_f32_dpp v81, v67, v66 quad_perm:[1,0,3,2] row_mask:0xf bank_mask:0xf bound_ctrl:1
	v_pk_fma_f32 v[6:7], v[34:35], v[76:77], v[72:73] op_sel_hi:[0,1,1] neg_lo:[1,0,0] neg_hi:[1,0,0]
	v_pk_fma_f32 v[8:9], v[34:35], v[76:77], v[74:75] op_sel:[1,0,0] op_sel_hi:[1,1,1] neg_lo:[1,0,0] neg_hi:[1,0,0]
	v_add_f32_dpp v82, v81, v81 quad_perm:[3,2,1,0] row_mask:0xf bank_mask:0xf bound_ctrl:1
	v_fma_f32 v83, v36, v94, v82
	v_fma_f32 v82, -v76, v95, v83
	ds_write_b32 v14, v82 offset:3072
	s_waitcnt lgkmcnt(1)
; #define LAS __attribute__((address_space(3)))
; template <int CTRL> __device__ __forceinline__ float dppf(float x) { return __builtin_bit_cast(float, __builtin_amdgcn_mov_dpp(__builtin_bit_cast(int, x), CTRL, 0xf, 0xf, true)); }
; __device__ __forceinline__ float sum16(float x) { x = sum8(x); x += dppf<0x140>(x); return x; }
; __device__ __forceinline__ void rwkv_item(LAS unsigned char* lds, int l, const bf16_t* PROJ, const bf16_t* LO, bf16_t* YR, float* BON, int b, int h, int qv) {
;     ...
;             for (int t = 0; t < CH; ++t) {
;                 const int tn = (t + 1) & (CH - 1);
;                 const LAS float* pn = pk + tn * 64;
;                 const f32x4 nkk = *(const LAS f32x4*)(pn), nwr = *(const LAS f32x4*)(pn + 2048), nw = *(const LAS f32x4*)(pn + 4096), nk = *(const LAS f32x4*)(pn + 6144), na = *(const LAS f32x4*)(pn + 8192);
;                 const float nv0 = pv[tn * 32], nv1 = pv[tn * 32 + 4]; const f32x2 nsc = *(const LAS f32x2*)(ps + 2 * tn);
;                 float sa[2], yp[2];
; #pragma unroll
;                 for (int c = 0; c < 2; ++c) { const f32x2 pa = S23[c] * kk4.hi + S01[c] * kk4.lo, pb = S23[c] * wr4.hi + S01[c] * wr4.lo; sa[c] = pa.x + pa.y; yp[c] = pb.x + pb.y; }
; #pragma unroll
;                 for (int c = 0; c < 2; ++c) { sa[c] = sum16(sa[c]); yp[c] += dppf<0xB1>(yp[c]); yp[c] += dppf<0x4E>(yp[c]); }
; #pragma unroll
;                 for (int c = 0; c < 2; ++c) {
;                     S01[c] = S01[c] * w4.lo + (k4.lo * vv[c] - a4.lo * sa[c]);
;                     S23[c] = S23[c] * w4.hi + (k4.hi * vv[c] - a4.hi * sa[c]);
;                     py[(t * 32 + 4 * c) * 4] = yp[c] + 0.25f * (vv[c] * sc.x - sa[c] * sc.y);
;                 }
;                 kk4 = nkk; wr4 = nwr; w4 = nw; k4 = nk; a4 = na; vv[0] = nv0; vv[1] = nv1; sc = nsc;
;             }
	v_pk_mul_f32 v[64:65], v[2:3], v[40:41] op_sel_hi:[1,0]
	v_pk_mul_f32 v[66:67], v[2:3], v[44:45] op_sel_hi:[1,0]
	v_pk_fma_f32 v[64:65], v[4:5], v[40:41], v[64:65] op_sel:[0,1,0] op_sel_hi:[1,1,1]
	v_pk_fma_f32 v[66:67], v[4:5], v[44:45], v[66:67] op_sel:[0,1,0] op_sel_hi:[1,1,1]
	v_pk_fma_f32 v[64:65], v[6:7], v[42:43], v[64:65] op_sel_hi:[1,0,1]
	v_pk_fma_f32 v[66:67], v[6:7], v[46:47], v[66:67] op_sel_hi:[1,0,1]
	v_pk_fma_f32 v[64:65], v[8:9], v[42:43], v[64:65] op_sel:[0,1,0] op_sel_hi:[1,1,1]
	v_pk_fma_f32 v[66:67], v[8:9], v[46:47], v[66:67] op_sel:[0,1,0] op_sel_hi:[1,1,1]
	ds_read_b128 v[16:19], v10 offset:2048
	v_add_f32_dpp v78, v65, v64 quad_perm:[1,0,3,2] row_mask:0xf bank_mask:0xf bound_ctrl:1
	ds_read_b128 v[20:23], v10 offset:10240
	ds_read_b128 v[24:27], v10 offset:18432
	v_add_f32_dpp v79, v78, v78 quad_perm:[3,2,1,0] row_mask:0xf bank_mask:0xf bound_ctrl:1
	ds_read_b128 v[28:31], v10 offset:26624
	ds_read_b128 v[32:35], v10 offset:34816
	v_add_f32_dpp v80, v79, v79 row_half_mirror row_mask:0xf bank_mask:0xf bound_ctrl:1
	ds_read_b32 v36, v11 offset:41984
	ds_read_b32 v37, v12 offset:41984
	v_add_f32_dpp v76, v80, v80 row_mirror row_mask:0xf bank_mask:0xf bound_ctrl:1
	v_pk_mul_f32 v[68:69], v[60:61], v[52:53] op_sel_hi:[1,0]
	v_pk_mul_f32 v[70:71], v[60:61], v[52:53] op_sel:[0,1] op_sel_hi:[1,1]
	v_mov_b32_dpp v77, v76 quad_perm:[1,0,3,2] row_mask:0xf bank_mask:0xf bound_ctrl:1
	v_pk_mul_f32 v[72:73], v[60:61], v[54:55] op_sel_hi:[1,0]
	v_pk_mul_f32 v[74:75], v[60:61], v[54:55] op_sel:[0,1] op_sel_hi:[1,1]
	v_pk_fma_f32 v[68:69], v[2:3], v[48:49], v[68:69] op_sel_hi:[1,0,1]
	v_pk_fma_f32 v[70:71], v[4:5], v[48:49], v[70:71] op_sel:[0,1,0] op_sel_hi:[1,1,1]
	v_pk_fma_f32 v[72:73], v[6:7], v[50:51], v[72:73] op_sel_hi:[1,0,1]
	v_pk_fma_f32 v[74:75], v[8:9], v[50:51], v[74:75] op_sel:[0,1,0] op_sel_hi:[1,1,1]
	v_pk_fma_f32 v[2:3], v[56:57], v[76:77], v[68:69] op_sel_hi:[0,1,1] neg_lo:[1,0,0] neg_hi:[1,0,0]
	v_pk_fma_f32 v[4:5], v[56:57], v[76:77], v[70:71] op_sel:[1,0,0] op_sel_hi:[1,1,1] neg_lo:[1,0,0] neg_hi:[1,0,0]
	v_add_f32_dpp v81, v67, v66 quad_perm:[1,0,3,2] row_mask:0xf bank_mask:0xf bound_ctrl:1
	v_pk_fma_f32 v[6:7], v[58:59], v[76:77], v[72:73] op_sel_hi:[0,1,1] neg_lo:[1,0,0] neg_hi:[1,0,0]
	v_pk_fma_f32 v[8:9], v[58:59], v[76:77], v[74:75] op_sel:[1,0,0] op_sel_hi:[1,1,1] neg_lo:[1,0,0] neg_hi:[1,0,0]
	v_add_f32_dpp v82, v81, v81 quad_perm:[3,2,1,0] row_mask:0xf bank_mask:0xf bound_ctrl:1
	v_fma_f32 v83, v60, v96, v82
	v_fma_f32 v82, -v76, v97, v83
	ds_write_b32 v14, v82 offset:3584
	s_waitcnt lgkmcnt(1)
	v_pk_mul_f32 v[64:65], v[2:3], v[16:17] op_sel_hi:[1,0]
	v_pk_mul_f32 v[66:67], v[2:3], v[20:21] op_sel_hi:[1,0]
	v_pk_fma_f32 v[64:65], v[4:5], v[16:17], v[64:65] op_sel:[0,1,0] op_sel_hi:[1,1,1]
	v_pk_fma_f32 v[66:67], v[4:5], v[20:21], v[66:67] op_sel:[0,1,0] op_sel_hi:[1,1,1]
	v_pk_fma_f32 v[64:65], v[6:7], v[18:19], v[64:65] op_sel_hi:[1,0,1]
	v_pk_fma_f32 v[66:67], v[6:7], v[22:23], v[66:67] op_sel_hi:[1,0,1]
	v_pk_fma_f32 v[64:65], v[8:9], v[18:19], v[64:65] op_sel:[0,1,0] op_sel_hi:[1,1,1]
	v_pk_fma_f32 v[66:67], v[8:9], v[22:23], v[66:67] op_sel:[0,1,0] op_sel_hi:[1,1,1]
	ds_read_b128 v[40:43], v10 offset:2304
	v_add_f32_dpp v78, v65, v64 quad_perm:[1,0,3,2] row_mask:0xf bank_mask:0xf bound_ctrl:1
	ds_read_b128 v[44:47], v10 offset:10496
	ds_read_b128 v[48:51], v10 offset:18688
	v_add_f32_dpp v79, v78, v78 quad_perm:[3,2,1,0] row_mask:0xf bank_mask:0xf bound_ctrl:1
	ds_read_b128 v[52:55], v10 offset:26880
	ds_read_b128 v[56:59], v10 offset:35072
	v_add_f32_dpp v80, v79, v79 row_half_mirror row_mask:0xf bank_mask:0xf bound_ctrl:1
	ds_read_b32 v60, v11 offset:42112
	ds_read_b32 v61, v12 offset:42112
	v_add_f32_dpp v76, v80, v80 row_mirror row_mask:0xf bank_mask:0xf bound_ctrl:1
	ds_read_b128 v[94:97], v100 offset:80
	v_pk_mul_f32 v[68:69], v[36:37], v[28:29] op_sel_hi:[1,0]
	v_pk_mul_f32 v[70:71], v[36:37], v[28:29] op_sel:[0,1] op_sel_hi:[1,1]
	v_mov_b32_dpp v77, v76 quad_perm:[1,0,3,2] row_mask:0xf bank_mask:0xf bound_ctrl:1
	v_pk_mul_f32 v[72:73], v[36:37], v[30:31] op_sel_hi:[1,0]
	v_pk_mul_f32 v[74:75], v[36:37], v[30:31] op_sel:[0,1] op_sel_hi:[1,1]
	v_pk_fma_f32 v[68:69], v[2:3], v[24:25], v[68:69] op_sel_hi:[1,0,1]
	v_pk_fma_f32 v[70:71], v[4:5], v[24:25], v[70:71] op_sel:[0,1,0] op_sel_hi:[1,1,1]
	v_pk_fma_f32 v[72:73], v[6:7], v[26:27], v[72:73] op_sel_hi:[1,0,1]
	v_pk_fma_f32 v[74:75], v[8:9], v[26:27], v[74:75] op_sel:[0,1,0] op_sel_hi:[1,1,1]
	v_pk_fma_f32 v[2:3], v[32:33], v[76:77], v[68:69] op_sel_hi:[0,1,1] neg_lo:[1,0,0] neg_hi:[1,0,0]
	v_pk_fma_f32 v[4:5], v[32:33], v[76:77], v[70:71] op_sel:[1,0,0] op_sel_hi:[1,1,1] neg_lo:[1,0,0] neg_hi:[1,0,0]
	v_add_f32_dpp v81, v67, v66 quad_perm:[1,0,3,2] row_mask:0xf bank_mask:0xf bound_ctrl:1
	v_pk_fma_f32 v[6:7], v[34:35], v[76:77], v[72:73] op_sel_hi:[0,1,1] neg_lo:[1,0,0] neg_hi:[1,0,0]
	v_pk_fma_f32 v[8:9], v[34:35], v[76:77], v[74:75] op_sel:[1,0,0] op_sel_hi:[1,1,1] neg_lo:[1,0,0] neg_hi:[1,0,0]
	v_add_f32_dpp v82, v81, v81 quad_perm:[3,2,1,0] row_mask:0xf bank_mask:0xf bound_ctrl:1
	v_fma_f32 v83, v36, v90, v82
	v_fma_f32 v82, -v76, v91, v83
	ds_write_b32 v14, v82 offset:4096
	s_waitcnt lgkmcnt(1)
; #define LAS __attribute__((address_space(3)))
; template <int CTRL> __device__ __forceinline__ float dppf(float x) { return __builtin_bit_cast(float, __builtin_amdgcn_mov_dpp(__builtin_bit_cast(int, x), CTRL, 0xf, 0xf, true)); }
; __device__ __forceinline__ float sum16(float x) { x = sum8(x); x += dppf<0x140>(x); return x; }
; __device__ __forceinline__ void rwkv_item(LAS unsigned char* lds, int l, const bf16_t* PROJ, const bf16_t* LO, bf16_t* YR, float* BON, int b, int h, int qv) {
;     ...
;             for (int t = 0; t < CH; ++t) {
;                 const int tn = (t + 1) & (CH - 1);
;                 const LAS float* pn = pk + tn * 64;
;                 const f32x4 nkk = *(const LAS f32x4*)(pn), nwr = *(const LAS f32x4*)(pn + 2048), nw = *(const LAS f32x4*)(pn + 4096), nk = *(const LAS f32x4*)(pn + 6144), na = *(const LAS f32x4*)(pn + 8192);
;                 const float nv0 = pv[tn * 32], nv1 = pv[tn * 32 + 4]; const f32x2 nsc = *(const LAS f32x2*)(ps + 2 * tn);
;                 float sa[2], yp[2];
; #pragma unroll
;                 for (int c = 0; c < 2; ++c) { const f32x2 pa = S23[c] * kk4.hi + S01[c] * kk4.lo, pb = S23[c] * wr4.hi + S01[c] * wr4.lo; sa[c] = pa.x + pa.y; yp[c] = pb.x + pb.y; }
; #pragma unroll
;                 for (int c = 0; c < 2; ++c) { sa[c] = sum16(sa[c]); yp[c] += dppf<0xB1>(yp[c]); yp[c] += dppf<0x4E>(yp[c]); }
; #pragma unroll
;                 for (int c = 0; c < 2; ++c) {
;                     S01[c] = S01[c] * w4.lo + (k4.lo * vv[c] - a4.lo * sa[c]);
;                     S23[c] = S23[c] * w4.hi + (k4.hi * vv[c] - a4.hi * sa[c]);
;                     py[(t * 32 + 4 * c) * 4] = yp[c] + 0.25f * (vv[c] * sc.x - sa[c] * sc.y);
;                 }
;                 kk4 = nkk; wr4 = nwr; w4 = nw; k4 = nk; a4 = na; vv[0] = nv0; vv[1] = nv1; sc = nsc;
;             }
	v_pk_mul_f32 v[64:65], v[2:3], v[40:41] op_sel_hi:[1,0]
	v_pk_mul_f32 v[66:67], v[2:3], v[44:45] op_sel_hi:[1,0]
	v_pk_fma_f32 v[64:65], v[4:5], v[40:41], v[64:65] op_sel:[0,1,0] op_sel_hi:[1,1,1]
	v_pk_fma_f32 v[66:67], v[4:5], v[44:45], v[66:67] op_sel:[0,1,0] op_sel_hi:[1,1,1]
	v_pk_fma_f32 v[64:65], v[6:7], v[42:43], v[64:65] op_sel_hi:[1,0,1]
	v_pk_fma_f32 v[66:67], v[6:7], v[46:47], v[66:67] op_sel_hi:[1,0,1]
	v_pk_fma_f32 v[64:65], v[8:9], v[42:43], v[64:65] op_sel:[0,1,0] op_sel_hi:[1,1,1]
	v_pk_fma_f32 v[66:67], v[8:9], v[46:47], v[66:67] op_sel:[0,1,0] op_sel_hi:[1,1,1]
	ds_read_b128 v[16:19], v10 offset:2560
	v_add_f32_dpp v78, v65, v64 quad_perm:[1,0,3,2] row_mask:0xf bank_mask:0xf bound_ctrl:1
	ds_read_b128 v[20:23], v10 offset:10752
	ds_read_b128 v[24:27], v10 offset:18944
	v_add_f32_dpp v79, v78, v78 quad_perm:[3,2,1,0] row_mask:0xf bank_mask:0xf bound_ctrl:1
	ds_read_b128 v[28:31], v10 offset:27136
	ds_read_b128 v[32:35], v10 offset:35328
	v_add_f32_dpp v80, v79, v79 row_half_mirror row_mask:0xf bank_mask:0xf bound_ctrl:1
	ds_read_b32 v36, v11 offset:42240
	ds_read_b32 v37, v12 offset:42240
	v_add_f32_dpp v76, v80, v80 row_mirror row_mask:0xf bank_mask:0xf bound_ctrl:1
	v_pk_mul_f32 v[68:69], v[60:61], v[52:53] op_sel_hi:[1,0]
	v_pk_mul_f32 v[70:71], v[60:61], v[52:53] op_sel:[0,1] op_sel_hi:[1,1]
	v_mov_b32_dpp v77, v76 quad_perm:[1,0,3,2] row_mask:0xf bank_mask:0xf bound_ctrl:1
	v_pk_mul_f32 v[72:73], v[60:61], v[54:55] op_sel_hi:[1,0]
	v_pk_mul_f32 v[74:75], v[60:61], v[54:55] op_sel:[0,1] op_sel_hi:[1,1]
	v_pk_fma_f32 v[68:69], v[2:3], v[48:49], v[68:69] op_sel_hi:[1,0,1]
	v_pk_fma_f32 v[70:71], v[4:5], v[48:49], v[70:71] op_sel:[0,1,0] op_sel_hi:[1,1,1]
	v_pk_fma_f32 v[72:73], v[6:7], v[50:51], v[72:73] op_sel_hi:[1,0,1]
	v_pk_fma_f32 v[74:75], v[8:9], v[50:51], v[74:75] op_sel:[0,1,0] op_sel_hi:[1,1,1]
	v_pk_fma_f32 v[2:3], v[56:57], v[76:77], v[68:69] op_sel_hi:[0,1,1] neg_lo:[1,0,0] neg_hi:[1,0,0]
	v_pk_fma_f32 v[4:5], v[56:57], v[76:77], v[70:71] op_sel:[1,0,0] op_sel_hi:[1,1,1] neg_lo:[1,0,0] neg_hi:[1,0,0]
	v_add_f32_dpp v81, v67, v66 quad_perm:[1,0,3,2] row_mask:0xf bank_mask:0xf bound_ctrl:1
	v_pk_fma_f32 v[6:7], v[58:59], v[76:77], v[72:73] op_sel_hi:[0,1,1] neg_lo:[1,0,0] neg_hi:[1,0,0]
	v_pk_fma_f32 v[8:9], v[58:59], v[76:77], v[74:75] op_sel:[1,0,0] op_sel_hi:[1,1,1] neg_lo:[1,0,0] neg_hi:[1,0,0]
	v_add_f32_dpp v82, v81, v81 quad_perm:[3,2,1,0] row_mask:0xf bank_mask:0xf bound_ctrl:1
	v_fma_f32 v83, v60, v92, v82
	v_fma_f32 v82, -v76, v93, v83
	ds_write_b32 v14, v82 offset:4608
	s_waitcnt lgkmcnt(1)
	v_pk_mul_f32 v[64:65], v[2:3], v[16:17] op_sel_hi:[1,0]
	v_pk_mul_f32 v[66:67], v[2:3], v[20:21] op_sel_hi:[1,0]
	v_pk_fma_f32 v[64:65], v[4:5], v[16:17], v[64:65] op_sel:[0,1,0] op_sel_hi:[1,1,1]
	v_pk_fma_f32 v[66:67], v[4:5], v[20:21], v[66:67] op_sel:[0,1,0] op_sel_hi:[1,1,1]
	v_pk_fma_f32 v[64:65], v[6:7], v[18:19], v[64:65] op_sel_hi:[1,0,1]
	v_pk_fma_f32 v[66:67], v[6:7], v[22:23], v[66:67] op_sel_hi:[1,0,1]
	v_pk_fma_f32 v[64:65], v[8:9], v[18:19], v[64:65] op_sel:[0,1,0] op_sel_hi:[1,1,1]
	v_pk_fma_f32 v[66:67], v[8:9], v[22:23], v[66:67] op_sel:[0,1,0] op_sel_hi:[1,1,1]
	ds_read_b128 v[40:43], v10 offset:2816
	v_add_f32_dpp v78, v65, v64 quad_perm:[1,0,3,2] row_mask:0xf bank_mask:0xf bound_ctrl:1
	ds_read_b128 v[44:47], v10 offset:11008
	ds_read_b128 v[48:51], v10 offset:19200
	v_add_f32_dpp v79, v78, v78 quad_perm:[3,2,1,0] row_mask:0xf bank_mask:0xf bound_ctrl:1
	ds_read_b128 v[52:55], v10 offset:27392
	ds_read_b128 v[56:59], v10 offset:35584
	v_add_f32_dpp v80, v79, v79 row_half_mirror row_mask:0xf bank_mask:0xf bound_ctrl:1
	ds_read_b32 v60, v11 offset:42368
	ds_read_b32 v61, v12 offset:42368
	v_add_f32_dpp v76, v80, v80 row_mirror row_mask:0xf bank_mask:0xf bound_ctrl:1
	ds_read_b128 v[90:93], v100 offset:96
	v_pk_mul_f32 v[68:69], v[36:37], v[28:29] op_sel_hi:[1,0]
	v_pk_mul_f32 v[70:71], v[36:37], v[28:29] op_sel:[0,1] op_sel_hi:[1,1]
	v_mov_b32_dpp v77, v76 quad_perm:[1,0,3,2] row_mask:0xf bank_mask:0xf bound_ctrl:1
	v_pk_mul_f32 v[72:73], v[36:37], v[30:31] op_sel_hi:[1,0]
	v_pk_mul_f32 v[74:75], v[36:37], v[30:31] op_sel:[0,1] op_sel_hi:[1,1]
	v_pk_fma_f32 v[68:69], v[2:3], v[24:25], v[68:69] op_sel_hi:[1,0,1]
	v_pk_fma_f32 v[70:71], v[4:5], v[24:25], v[70:71] op_sel:[0,1,0] op_sel_hi:[1,1,1]
	v_pk_fma_f32 v[72:73], v[6:7], v[26:27], v[72:73] op_sel_hi:[1,0,1]
	v_pk_fma_f32 v[74:75], v[8:9], v[26:27], v[74:75] op_sel:[0,1,0] op_sel_hi:[1,1,1]
	v_pk_fma_f32 v[2:3], v[32:33], v[76:77], v[68:69] op_sel_hi:[0,1,1] neg_lo:[1,0,0] neg_hi:[1,0,0]
	v_pk_fma_f32 v[4:5], v[32:33], v[76:77], v[70:71] op_sel:[1,0,0] op_sel_hi:[1,1,1] neg_lo:[1,0,0] neg_hi:[1,0,0]
	v_add_f32_dpp v81, v67, v66 quad_perm:[1,0,3,2] row_mask:0xf bank_mask:0xf bound_ctrl:1
	v_pk_fma_f32 v[6:7], v[34:35], v[76:77], v[72:73] op_sel_hi:[0,1,1] neg_lo:[1,0,0] neg_hi:[1,0,0]
	v_pk_fma_f32 v[8:9], v[34:35], v[76:77], v[74:75] op_sel:[1,0,0] op_sel_hi:[1,1,1] neg_lo:[1,0,0] neg_hi:[1,0,0]
	v_add_f32_dpp v82, v81, v81 quad_perm:[3,2,1,0] row_mask:0xf bank_mask:0xf bound_ctrl:1
	v_fma_f32 v83, v36, v94, v82
	v_fma_f32 v82, -v76, v95, v83
	ds_write_b32 v14, v82 offset:5120
	s_waitcnt lgkmcnt(1)
; #define LAS __attribute__((address_space(3)))
; template <int CTRL> __device__ __forceinline__ float dppf(float x) { return __builtin_bit_cast(float, __builtin_amdgcn_mov_dpp(__builtin_bit_cast(int, x), CTRL, 0xf, 0xf, true)); }
; __device__ __forceinline__ float sum16(float x) { x = sum8(x); x += dppf<0x140>(x); return x; }
; __device__ __forceinline__ void rwkv_item(LAS unsigned char* lds, int l, const bf16_t* PROJ, const bf16_t* LO, bf16_t* YR, float* BON, int b, int h, int qv) {
;     ...
;             for (int t = 0; t < CH; ++t) {
;                 const int tn = (t + 1) & (CH - 1);
;                 const LAS float* pn = pk + tn * 64;
;                 const f32x4 nkk = *(const LAS f32x4*)(pn), nwr = *(const LAS f32x4*)(pn + 2048), nw = *(const LAS f32x4*)(pn + 4096), nk = *(const LAS f32x4*)(pn + 6144), na = *(const LAS f32x4*)(pn + 8192);
;                 const float nv0 = pv[tn * 32], nv1 = pv[tn * 32 + 4]; const f32x2 nsc = *(const LAS f32x2*)(ps + 2 * tn);
;                 float sa[2], yp[2];
; #pragma unroll
;                 for (int c = 0; c < 2; ++c) { const f32x2 pa = S23[c] * kk4.hi + S01[c] * kk4.lo, pb = S23[c] * wr4.hi + S01[c] * wr4.lo; sa[c] = pa.x + pa.y; yp[c] = pb.x + pb.y; }
; #pragma unroll
;                 for (int c = 0; c < 2; ++c) { sa[c] = sum16(sa[c]); yp[c] += dppf<0xB1>(yp[c]); yp[c] += dppf<0x4E>(yp[c]); }
; #pragma unroll
;                 for (int c = 0; c < 2; ++c) {
;                     S01[c] = S01[c] * w4.lo + (k4.lo * vv[c] - a4.lo * sa[c]);
;                     S23[c] = S23[c] * w4.hi + (k4.hi * vv[c] - a4.hi * sa[c]);
;                     py[(t * 32 + 4 * c) * 4] = yp[c] + 0.25f * (vv[c] * sc.x - sa[c] * sc.y);
;                 }
;                 kk4 = nkk; wr4 = nwr; w4 = nw; k4 = nk; a4 = na; vv[0] = nv0; vv[1] = nv1; sc = nsc;
;             }
	v_pk_mul_f32 v[64:65], v[2:3], v[40:41] op_sel_hi:[1,0]
	v_pk_mul_f32 v[66:67], v[2:3], v[44:45] op_sel_hi:[1,0]
	v_pk_fma_f32 v[64:65], v[4:5], v[40:41], v[64:65] op_sel:[0,1,0] op_sel_hi:[1,1,1]
	v_pk_fma_f32 v[66:67], v[4:5], v[44:45], v[66:67] op_sel:[0,1,0] op_sel_hi:[1,1,1]
	v_pk_fma_f32 v[64:65], v[6:7], v[42:43], v[64:65] op_sel_hi:[1,0,1]
	v_pk_fma_f32 v[66:67], v[6:7], v[46:47], v[66:67] op_sel_hi:[1,0,1]
	v_pk_fma_f32 v[64:65], v[8:9], v[42:43], v[64:65] op_sel:[0,1,0] op_sel_hi:[1,1,1]
	v_pk_fma_f32 v[66:67], v[8:9], v[46:47], v[66:67] op_sel:[0,1,0] op_sel_hi:[1,1,1]
	ds_read_b128 v[16:19], v10 offset:3072
	v_add_f32_dpp v78, v65, v64 quad_perm:[1,0,3,2] row_mask:0xf bank_mask:0xf bound_ctrl:1
	ds_read_b128 v[20:23], v10 offset:11264
	ds_read_b128 v[24:27], v10 offset:19456
	v_add_f32_dpp v79, v78, v78 quad_perm:[3,2,1,0] row_mask:0xf bank_mask:0xf bound_ctrl:1
	ds_read_b128 v[28:31], v10 offset:27648
	ds_read_b128 v[32:35], v10 offset:35840
	v_add_f32_dpp v80, v79, v79 row_half_mirror row_mask:0xf bank_mask:0xf bound_ctrl:1
	ds_read_b32 v36, v11 offset:42496
	ds_read_b32 v37, v12 offset:42496
	v_add_f32_dpp v76, v80, v80 row_mirror row_mask:0xf bank_mask:0xf bound_ctrl:1
	v_pk_mul_f32 v[68:69], v[60:61], v[52:53] op_sel_hi:[1,0]
	v_pk_mul_f32 v[70:71], v[60:61], v[52:53] op_sel:[0,1] op_sel_hi:[1,1]
	v_mov_b32_dpp v77, v76 quad_perm:[1,0,3,2] row_mask:0xf bank_mask:0xf bound_ctrl:1
	v_pk_mul_f32 v[72:73], v[60:61], v[54:55] op_sel_hi:[1,0]
	v_pk_mul_f32 v[74:75], v[60:61], v[54:55] op_sel:[0,1] op_sel_hi:[1,1]
	v_pk_fma_f32 v[68:69], v[2:3], v[48:49], v[68:69] op_sel_hi:[1,0,1]
	v_pk_fma_f32 v[70:71], v[4:5], v[48:49], v[70:71] op_sel:[0,1,0] op_sel_hi:[1,1,1]
	v_pk_fma_f32 v[72:73], v[6:7], v[50:51], v[72:73] op_sel_hi:[1,0,1]
	v_pk_fma_f32 v[74:75], v[8:9], v[50:51], v[74:75] op_sel:[0,1,0] op_sel_hi:[1,1,1]
	v_pk_fma_f32 v[2:3], v[56:57], v[76:77], v[68:69] op_sel_hi:[0,1,1] neg_lo:[1,0,0] neg_hi:[1,0,0]
	v_pk_fma_f32 v[4:5], v[56:57], v[76:77], v[70:71] op_sel:[1,0,0] op_sel_hi:[1,1,1] neg_lo:[1,0,0] neg_hi:[1,0,0]
	v_add_f32_dpp v81, v67, v66 quad_perm:[1,0,3,2] row_mask:0xf bank_mask:0xf bound_ctrl:1
	v_pk_fma_f32 v[6:7], v[58:59], v[76:77], v[72:73] op_sel_hi:[0,1,1] neg_lo:[1,0,0] neg_hi:[1,0,0]
	v_pk_fma_f32 v[8:9], v[58:59], v[76:77], v[74:75] op_sel:[1,0,0] op_sel_hi:[1,1,1] neg_lo:[1,0,0] neg_hi:[1,0,0]
	v_add_f32_dpp v82, v81, v81 quad_perm:[3,2,1,0] row_mask:0xf bank_mask:0xf bound_ctrl:1
	v_fma_f32 v83, v60, v96, v82
	v_fma_f32 v82, -v76, v97, v83
	ds_write_b32 v14, v82 offset:5632
	s_waitcnt lgkmcnt(1)
	v_pk_mul_f32 v[64:65], v[2:3], v[16:17] op_sel_hi:[1,0]
	v_pk_mul_f32 v[66:67], v[2:3], v[20:21] op_sel_hi:[1,0]
	v_pk_fma_f32 v[64:65], v[4:5], v[16:17], v[64:65] op_sel:[0,1,0] op_sel_hi:[1,1,1]
	v_pk_fma_f32 v[66:67], v[4:5], v[20:21], v[66:67] op_sel:[0,1,0] op_sel_hi:[1,1,1]
	v_pk_fma_f32 v[64:65], v[6:7], v[18:19], v[64:65] op_sel_hi:[1,0,1]
	v_pk_fma_f32 v[66:67], v[6:7], v[22:23], v[66:67] op_sel_hi:[1,0,1]
	v_pk_fma_f32 v[64:65], v[8:9], v[18:19], v[64:65] op_sel:[0,1,0] op_sel_hi:[1,1,1]
	v_pk_fma_f32 v[66:67], v[8:9], v[22:23], v[66:67] op_sel:[0,1,0] op_sel_hi:[1,1,1]
	ds_read_b128 v[40:43], v10 offset:3328
	v_add_f32_dpp v78, v65, v64 quad_perm:[1,0,3,2] row_mask:0xf bank_mask:0xf bound_ctrl:1
	ds_read_b128 v[44:47], v10 offset:11520
	ds_read_b128 v[48:51], v10 offset:19712
	v_add_f32_dpp v79, v78, v78 quad_perm:[3,2,1,0] row_mask:0xf bank_mask:0xf bound_ctrl:1
	ds_read_b128 v[52:55], v10 offset:27904
	ds_read_b128 v[56:59], v10 offset:36096
	v_add_f32_dpp v80, v79, v79 row_half_mirror row_mask:0xf bank_mask:0xf bound_ctrl:1
	ds_read_b32 v60, v11 offset:42624
	ds_read_b32 v61, v12 offset:42624
	v_add_f32_dpp v76, v80, v80 row_mirror row_mask:0xf bank_mask:0xf bound_ctrl:1
	ds_read_b128 v[94:97], v100 offset:112
	v_pk_mul_f32 v[68:69], v[36:37], v[28:29] op_sel_hi:[1,0]
	v_pk_mul_f32 v[70:71], v[36:37], v[28:29] op_sel:[0,1] op_sel_hi:[1,1]
	v_mov_b32_dpp v77, v76 quad_perm:[1,0,3,2] row_mask:0xf bank_mask:0xf bound_ctrl:1
	v_pk_mul_f32 v[72:73], v[36:37], v[30:31] op_sel_hi:[1,0]
	v_pk_mul_f32 v[74:75], v[36:37], v[30:31] op_sel:[0,1] op_sel_hi:[1,1]
	v_pk_fma_f32 v[68:69], v[2:3], v[24:25], v[68:69] op_sel_hi:[1,0,1]
	v_pk_fma_f32 v[70:71], v[4:5], v[24:25], v[70:71] op_sel:[0,1,0] op_sel_hi:[1,1,1]
	v_pk_fma_f32 v[72:73], v[6:7], v[26:27], v[72:73] op_sel_hi:[1,0,1]
	v_pk_fma_f32 v[74:75], v[8:9], v[26:27], v[74:75] op_sel:[0,1,0] op_sel_hi:[1,1,1]
	v_pk_fma_f32 v[2:3], v[32:33], v[76:77], v[68:69] op_sel_hi:[0,1,1] neg_lo:[1,0,0] neg_hi:[1,0,0]
	v_pk_fma_f32 v[4:5], v[32:33], v[76:77], v[70:71] op_sel:[1,0,0] op_sel_hi:[1,1,1] neg_lo:[1,0,0] neg_hi:[1,0,0]
	v_add_f32_dpp v81, v67, v66 quad_perm:[1,0,3,2] row_mask:0xf bank_mask:0xf bound_ctrl:1
	v_pk_fma_f32 v[6:7], v[34:35], v[76:77], v[72:73] op_sel_hi:[0,1,1] neg_lo:[1,0,0] neg_hi:[1,0,0]
	v_pk_fma_f32 v[8:9], v[34:35], v[76:77], v[74:75] op_sel:[1,0,0] op_sel_hi:[1,1,1] neg_lo:[1,0,0] neg_hi:[1,0,0]
	v_add_f32_dpp v82, v81, v81 quad_perm:[3,2,1,0] row_mask:0xf bank_mask:0xf bound_ctrl:1
	v_fma_f32 v83, v36, v90, v82
	v_fma_f32 v82, -v76, v91, v83
	ds_write_b32 v14, v82 offset:6144
	s_waitcnt lgkmcnt(1)
; #define LAS __attribute__((address_space(3)))
; template <int CTRL> __device__ __forceinline__ float dppf(float x) { return __builtin_bit_cast(float, __builtin_amdgcn_mov_dpp(__builtin_bit_cast(int, x), CTRL, 0xf, 0xf, true)); }
; __device__ __forceinline__ float sum16(float x) { x = sum8(x); x += dppf<0x140>(x); return x; }
; __device__ __forceinline__ void rwkv_item(LAS unsigned char* lds, int l, const bf16_t* PROJ, const bf16_t* LO, bf16_t* YR, float* BON, int b, int h, int qv) {
;     ...
;             for (int t = 0; t < CH; ++t) {
;                 const int tn = (t + 1) & (CH - 1);
;                 const LAS float* pn = pk + tn * 64;
;                 const f32x4 nkk = *(const LAS f32x4*)(pn), nwr = *(const LAS f32x4*)(pn + 2048), nw = *(const LAS f32x4*)(pn + 4096), nk = *(const LAS f32x4*)(pn + 6144), na = *(const LAS f32x4*)(pn + 8192);
;                 const float nv0 = pv[tn * 32], nv1 = pv[tn * 32 + 4]; const f32x2 nsc = *(const LAS f32x2*)(ps + 2 * tn);
;                 float sa[2], yp[2];
; #pragma unroll
;                 for (int c = 0; c < 2; ++c) { const f32x2 pa = S23[c] * kk4.hi + S01[c] * kk4.lo, pb = S23[c] * wr4.hi + S01[c] * wr4.lo; sa[c] = pa.x + pa.y; yp[c] = pb.x + pb.y; }
; #pragma unroll
;                 for (int c = 0; c < 2; ++c) { sa[c] = sum16(sa[c]); yp[c] += dppf<0xB1>(yp[c]); yp[c] += dppf<0x4E>(yp[c]); }
; #pragma unroll
;                 for (int c = 0; c < 2; ++c) {
;                     S01[c] = S01[c] * w4.lo + (k4.lo * vv[c] - a4.lo * sa[c]);
;                     S23[c] = S23[c] * w4.hi + (k4.hi * vv[c] - a4.hi * sa[c]);
;                     py[(t * 32 + 4 * c) * 4] = yp[c] + 0.25f * (vv[c] * sc.x - sa[c] * sc.y);
;                 }
;                 kk4 = nkk; wr4 = nwr; w4 = nw; k4 = nk; a4 = na; vv[0] = nv0; vv[1] = nv1; sc = nsc;
;             }
	v_pk_mul_f32 v[64:65], v[2:3], v[40:41] op_sel_hi:[1,0]
	v_pk_mul_f32 v[66:67], v[2:3], v[44:45] op_sel_hi:[1,0]
	v_pk_fma_f32 v[64:65], v[4:5], v[40:41], v[64:65] op_sel:[0,1,0] op_sel_hi:[1,1,1]
	v_pk_fma_f32 v[66:67], v[4:5], v[44:45], v[66:67] op_sel:[0,1,0] op_sel_hi:[1,1,1]
	v_pk_fma_f32 v[64:65], v[6:7], v[42:43], v[64:65] op_sel_hi:[1,0,1]
	v_pk_fma_f32 v[66:67], v[6:7], v[46:47], v[66:67] op_sel_hi:[1,0,1]
	v_pk_fma_f32 v[64:65], v[8:9], v[42:43], v[64:65] op_sel:[0,1,0] op_sel_hi:[1,1,1]
	v_pk_fma_f32 v[66:67], v[8:9], v[46:47], v[66:67] op_sel:[0,1,0] op_sel_hi:[1,1,1]
	ds_read_b128 v[16:19], v10 offset:3584
	v_add_f32_dpp v78, v65, v64 quad_perm:[1,0,3,2] row_mask:0xf bank_mask:0xf bound_ctrl:1
	ds_read_b128 v[20:23], v10 offset:11776
	ds_read_b128 v[24:27], v10 offset:19968
	v_add_f32_dpp v79, v78, v78 quad_perm:[3,2,1,0] row_mask:0xf bank_mask:0xf bound_ctrl:1
	ds_read_b128 v[28:31], v10 offset:28160
	ds_read_b128 v[32:35], v10 offset:36352
	v_add_f32_dpp v80, v79, v79 row_half_mirror row_mask:0xf bank_mask:0xf bound_ctrl:1
	ds_read_b32 v36, v11 offset:42752
	ds_read_b32 v37, v12 offset:42752
	v_add_f32_dpp v76, v80, v80 row_mirror row_mask:0xf bank_mask:0xf bound_ctrl:1
	v_pk_mul_f32 v[68:69], v[60:61], v[52:53] op_sel_hi:[1,0]
	v_pk_mul_f32 v[70:71], v[60:61], v[52:53] op_sel:[0,1] op_sel_hi:[1,1]
	v_mov_b32_dpp v77, v76 quad_perm:[1,0,3,2] row_mask:0xf bank_mask:0xf bound_ctrl:1
	v_pk_mul_f32 v[72:73], v[60:61], v[54:55] op_sel_hi:[1,0]
	v_pk_mul_f32 v[74:75], v[60:61], v[54:55] op_sel:[0,1] op_sel_hi:[1,1]
	v_pk_fma_f32 v[68:69], v[2:3], v[48:49], v[68:69] op_sel_hi:[1,0,1]
	v_pk_fma_f32 v[70:71], v[4:5], v[48:49], v[70:71] op_sel:[0,1,0] op_sel_hi:[1,1,1]
	v_pk_fma_f32 v[72:73], v[6:7], v[50:51], v[72:73] op_sel_hi:[1,0,1]
	v_pk_fma_f32 v[74:75], v[8:9], v[50:51], v[74:75] op_sel:[0,1,0] op_sel_hi:[1,1,1]
	v_pk_fma_f32 v[2:3], v[56:57], v[76:77], v[68:69] op_sel_hi:[0,1,1] neg_lo:[1,0,0] neg_hi:[1,0,0]
	v_pk_fma_f32 v[4:5], v[56:57], v[76:77], v[70:71] op_sel:[1,0,0] op_sel_hi:[1,1,1] neg_lo:[1,0,0] neg_hi:[1,0,0]
	v_add_f32_dpp v81, v67, v66 quad_perm:[1,0,3,2] row_mask:0xf bank_mask:0xf bound_ctrl:1
	v_pk_fma_f32 v[6:7], v[58:59], v[76:77], v[72:73] op_sel_hi:[0,1,1] neg_lo:[1,0,0] neg_hi:[1,0,0]
	v_pk_fma_f32 v[8:9], v[58:59], v[76:77], v[74:75] op_sel:[1,0,0] op_sel_hi:[1,1,1] neg_lo:[1,0,0] neg_hi:[1,0,0]
	v_add_f32_dpp v82, v81, v81 quad_perm:[3,2,1,0] row_mask:0xf bank_mask:0xf bound_ctrl:1
	v_fma_f32 v83, v60, v92, v82
	v_fma_f32 v82, -v76, v93, v83
	ds_write_b32 v14, v82 offset:6656
	s_waitcnt lgkmcnt(1)
	v_pk_mul_f32 v[64:65], v[2:3], v[16:17] op_sel_hi:[1,0]
	v_pk_mul_f32 v[66:67], v[2:3], v[20:21] op_sel_hi:[1,0]
	v_pk_fma_f32 v[64:65], v[4:5], v[16:17], v[64:65] op_sel:[0,1,0] op_sel_hi:[1,1,1]
	v_pk_fma_f32 v[66:67], v[4:5], v[20:21], v[66:67] op_sel:[0,1,0] op_sel_hi:[1,1,1]
	v_pk_fma_f32 v[64:65], v[6:7], v[18:19], v[64:65] op_sel_hi:[1,0,1]
	v_pk_fma_f32 v[66:67], v[6:7], v[22:23], v[66:67] op_sel_hi:[1,0,1]
	v_pk_fma_f32 v[64:65], v[8:9], v[18:19], v[64:65] op_sel:[0,1,0] op_sel_hi:[1,1,1]
	v_pk_fma_f32 v[66:67], v[8:9], v[22:23], v[66:67] op_sel:[0,1,0] op_sel_hi:[1,1,1]
	ds_read_b128 v[40:43], v10 offset:3840
	v_add_f32_dpp v78, v65, v64 quad_perm:[1,0,3,2] row_mask:0xf bank_mask:0xf bound_ctrl:1
	ds_read_b128 v[44:47], v10 offset:12032
	ds_read_b128 v[48:51], v10 offset:20224
	v_add_f32_dpp v79, v78, v78 quad_perm:[3,2,1,0] row_mask:0xf bank_mask:0xf bound_ctrl:1
	ds_read_b128 v[52:55], v10 offset:28416
	ds_read_b128 v[56:59], v10 offset:36608
	v_add_f32_dpp v80, v79, v79 row_half_mirror row_mask:0xf bank_mask:0xf bound_ctrl:1
	ds_read_b32 v60, v11 offset:42880
	ds_read_b32 v61, v12 offset:42880
	v_add_f32_dpp v76, v80, v80 row_mirror row_mask:0xf bank_mask:0xf bound_ctrl:1
	ds_read_b128 v[90:93], v100 offset:128
	v_pk_mul_f32 v[68:69], v[36:37], v[28:29] op_sel_hi:[1,0]
	v_pk_mul_f32 v[70:71], v[36:37], v[28:29] op_sel:[0,1] op_sel_hi:[1,1]
	v_mov_b32_dpp v77, v76 quad_perm:[1,0,3,2] row_mask:0xf bank_mask:0xf bound_ctrl:1
	v_pk_mul_f32 v[72:73], v[36:37], v[30:31] op_sel_hi:[1,0]
	v_pk_mul_f32 v[74:75], v[36:37], v[30:31] op_sel:[0,1] op_sel_hi:[1,1]
	v_pk_fma_f32 v[68:69], v[2:3], v[24:25], v[68:69] op_sel_hi:[1,0,1]
	v_pk_fma_f32 v[70:71], v[4:5], v[24:25], v[70:71] op_sel:[0,1,0] op_sel_hi:[1,1,1]
	v_pk_fma_f32 v[72:73], v[6:7], v[26:27], v[72:73] op_sel_hi:[1,0,1]
	v_pk_fma_f32 v[74:75], v[8:9], v[26:27], v[74:75] op_sel:[0,1,0] op_sel_hi:[1,1,1]
	v_pk_fma_f32 v[2:3], v[32:33], v[76:77], v[68:69] op_sel_hi:[0,1,1] neg_lo:[1,0,0] neg_hi:[1,0,0]
	v_pk_fma_f32 v[4:5], v[32:33], v[76:77], v[70:71] op_sel:[1,0,0] op_sel_hi:[1,1,1] neg_lo:[1,0,0] neg_hi:[1,0,0]
	v_add_f32_dpp v81, v67, v66 quad_perm:[1,0,3,2] row_mask:0xf bank_mask:0xf bound_ctrl:1
	v_pk_fma_f32 v[6:7], v[34:35], v[76:77], v[72:73] op_sel_hi:[0,1,1] neg_lo:[1,0,0] neg_hi:[1,0,0]
	v_pk_fma_f32 v[8:9], v[34:35], v[76:77], v[74:75] op_sel:[1,0,0] op_sel_hi:[1,1,1] neg_lo:[1,0,0] neg_hi:[1,0,0]
	v_add_f32_dpp v82, v81, v81 quad_perm:[3,2,1,0] row_mask:0xf bank_mask:0xf bound_ctrl:1
	v_fma_f32 v83, v36, v94, v82
	v_fma_f32 v82, -v76, v95, v83
	ds_write_b32 v14, v82 offset:7168
	s_waitcnt lgkmcnt(1)
; #define LAS __attribute__((address_space(3)))
; template <int CTRL> __device__ __forceinline__ float dppf(float x) { return __builtin_bit_cast(float, __builtin_amdgcn_mov_dpp(__builtin_bit_cast(int, x), CTRL, 0xf, 0xf, true)); }
; __device__ __forceinline__ float sum16(float x) { x = sum8(x); x += dppf<0x140>(x); return x; }
; __device__ __forceinline__ void rwkv_item(LAS unsigned char* lds, int l, const bf16_t* PROJ, const bf16_t* LO, bf16_t* YR, float* BON, int b, int h, int qv) {
;     ...
;             for (int t = 0; t < CH; ++t) {
;                 const int tn = (t + 1) & (CH - 1);
;                 const LAS float* pn = pk + tn * 64;
;                 const f32x4 nkk = *(const LAS f32x4*)(pn), nwr = *(const LAS f32x4*)(pn + 2048), nw = *(const LAS f32x4*)(pn + 4096), nk = *(const LAS f32x4*)(pn + 6144), na = *(const LAS f32x4*)(pn + 8192);
;                 const float nv0 = pv[tn * 32], nv1 = pv[tn * 32 + 4]; const f32x2 nsc = *(const LAS f32x2*)(ps + 2 * tn);
;                 float sa[2], yp[2];
; #pragma unroll
;                 for (int c = 0; c < 2; ++c) { const f32x2 pa = S23[c] * kk4.hi + S01[c] * kk4.lo, pb = S23[c] * wr4.hi + S01[c] * wr4.lo; sa[c] = pa.x + pa.y; yp[c] = pb.x + pb.y; }
; #pragma unroll
;                 for (int c = 0; c < 2; ++c) { sa[c] = sum16(sa[c]); yp[c] += dppf<0xB1>(yp[c]); yp[c] += dppf<0x4E>(yp[c]); }
; #pragma unroll
;                 for (int c = 0; c < 2; ++c) {
;                     S01[c] = S01[c] * w4.lo + (k4.lo * vv[c] - a4.lo * sa[c]);
;                     S23[c] = S23[c] * w4.hi + (k4.hi * vv[c] - a4.hi * sa[c]);
;                     py[(t * 32 + 4 * c) * 4] = yp[c] + 0.25f * (vv[c] * sc.x - sa[c] * sc.y);
;                 }
;                 kk4 = nkk; wr4 = nwr; w4 = nw; k4 = nk; a4 = na; vv[0] = nv0; vv[1] = nv1; sc = nsc;
;             }
	v_pk_mul_f32 v[64:65], v[2:3], v[40:41] op_sel_hi:[1,0]
	v_pk_mul_f32 v[66:67], v[2:3], v[44:45] op_sel_hi:[1,0]
	v_pk_fma_f32 v[64:65], v[4:5], v[40:41], v[64:65] op_sel:[0,1,0] op_sel_hi:[1,1,1]
	v_pk_fma_f32 v[66:67], v[4:5], v[44:45], v[66:67] op_sel:[0,1,0] op_sel_hi:[1,1,1]
	v_pk_fma_f32 v[64:65], v[6:7], v[42:43], v[64:65] op_sel_hi:[1,0,1]
	v_pk_fma_f32 v[66:67], v[6:7], v[46:47], v[66:67] op_sel_hi:[1,0,1]
	v_pk_fma_f32 v[64:65], v[8:9], v[42:43], v[64:65] op_sel:[0,1,0] op_sel_hi:[1,1,1]
	v_pk_fma_f32 v[66:67], v[8:9], v[46:47], v[66:67] op_sel:[0,1,0] op_sel_hi:[1,1,1]
	ds_read_b128 v[16:19], v10 offset:4096
	v_add_f32_dpp v78, v65, v64 quad_perm:[1,0,3,2] row_mask:0xf bank_mask:0xf bound_ctrl:1
	ds_read_b128 v[20:23], v10 offset:12288
	ds_read_b128 v[24:27], v10 offset:20480
	v_add_f32_dpp v79, v78, v78 quad_perm:[3,2,1,0] row_mask:0xf bank_mask:0xf bound_ctrl:1
	ds_read_b128 v[28:31], v10 offset:28672
	ds_read_b128 v[32:35], v10 offset:36864
	v_add_f32_dpp v80, v79, v79 row_half_mirror row_mask:0xf bank_mask:0xf bound_ctrl:1
	ds_read_b32 v36, v11 offset:43008
	ds_read_b32 v37, v12 offset:43008
	v_add_f32_dpp v76, v80, v80 row_mirror row_mask:0xf bank_mask:0xf bound_ctrl:1
	v_pk_mul_f32 v[68:69], v[60:61], v[52:53] op_sel_hi:[1,0]
	v_pk_mul_f32 v[70:71], v[60:61], v[52:53] op_sel:[0,1] op_sel_hi:[1,1]
	v_mov_b32_dpp v77, v76 quad_perm:[1,0,3,2] row_mask:0xf bank_mask:0xf bound_ctrl:1
	v_pk_mul_f32 v[72:73], v[60:61], v[54:55] op_sel_hi:[1,0]
	v_pk_mul_f32 v[74:75], v[60:61], v[54:55] op_sel:[0,1] op_sel_hi:[1,1]
	v_pk_fma_f32 v[68:69], v[2:3], v[48:49], v[68:69] op_sel_hi:[1,0,1]
	v_pk_fma_f32 v[70:71], v[4:5], v[48:49], v[70:71] op_sel:[0,1,0] op_sel_hi:[1,1,1]
	v_pk_fma_f32 v[72:73], v[6:7], v[50:51], v[72:73] op_sel_hi:[1,0,1]
	v_pk_fma_f32 v[74:75], v[8:9], v[50:51], v[74:75] op_sel:[0,1,0] op_sel_hi:[1,1,1]
	v_pk_fma_f32 v[2:3], v[56:57], v[76:77], v[68:69] op_sel_hi:[0,1,1] neg_lo:[1,0,0] neg_hi:[1,0,0]
	v_pk_fma_f32 v[4:5], v[56:57], v[76:77], v[70:71] op_sel:[1,0,0] op_sel_hi:[1,1,1] neg_lo:[1,0,0] neg_hi:[1,0,0]
	v_add_f32_dpp v81, v67, v66 quad_perm:[1,0,3,2] row_mask:0xf bank_mask:0xf bound_ctrl:1
	v_pk_fma_f32 v[6:7], v[58:59], v[76:77], v[72:73] op_sel_hi:[0,1,1] neg_lo:[1,0,0] neg_hi:[1,0,0]
	v_pk_fma_f32 v[8:9], v[58:59], v[76:77], v[74:75] op_sel:[1,0,0] op_sel_hi:[1,1,1] neg_lo:[1,0,0] neg_hi:[1,0,0]
	v_add_f32_dpp v82, v81, v81 quad_perm:[3,2,1,0] row_mask:0xf bank_mask:0xf bound_ctrl:1
	v_fma_f32 v83, v60, v96, v82
	v_fma_f32 v82, -v76, v97, v83
	ds_write_b32 v14, v82 offset:7680
	s_waitcnt lgkmcnt(1)
	v_pk_mul_f32 v[64:65], v[2:3], v[16:17] op_sel_hi:[1,0]
	v_pk_mul_f32 v[66:67], v[2:3], v[20:21] op_sel_hi:[1,0]
	v_pk_fma_f32 v[64:65], v[4:5], v[16:17], v[64:65] op_sel:[0,1,0] op_sel_hi:[1,1,1]
	v_pk_fma_f32 v[66:67], v[4:5], v[20:21], v[66:67] op_sel:[0,1,0] op_sel_hi:[1,1,1]
	v_pk_fma_f32 v[64:65], v[6:7], v[18:19], v[64:65] op_sel_hi:[1,0,1]
	v_pk_fma_f32 v[66:67], v[6:7], v[22:23], v[66:67] op_sel_hi:[1,0,1]
	v_pk_fma_f32 v[64:65], v[8:9], v[18:19], v[64:65] op_sel:[0,1,0] op_sel_hi:[1,1,1]
	v_pk_fma_f32 v[66:67], v[8:9], v[22:23], v[66:67] op_sel:[0,1,0] op_sel_hi:[1,1,1]
	ds_read_b128 v[40:43], v10 offset:4352
	v_add_f32_dpp v78, v65, v64 quad_perm:[1,0,3,2] row_mask:0xf bank_mask:0xf bound_ctrl:1
	ds_read_b128 v[44:47], v10 offset:12544
	ds_read_b128 v[48:51], v10 offset:20736
	v_add_f32_dpp v79, v78, v78 quad_perm:[3,2,1,0] row_mask:0xf bank_mask:0xf bound_ctrl:1
	ds_read_b128 v[52:55], v10 offset:28928
	ds_read_b128 v[56:59], v10 offset:37120
	v_add_f32_dpp v80, v79, v79 row_half_mirror row_mask:0xf bank_mask:0xf bound_ctrl:1
	ds_read_b32 v60, v11 offset:43136
	ds_read_b32 v61, v12 offset:43136
	v_add_f32_dpp v76, v80, v80 row_mirror row_mask:0xf bank_mask:0xf bound_ctrl:1
	ds_read_b128 v[94:97], v100 offset:144
	v_pk_mul_f32 v[68:69], v[36:37], v[28:29] op_sel_hi:[1,0]
	v_pk_mul_f32 v[70:71], v[36:37], v[28:29] op_sel:[0,1] op_sel_hi:[1,1]
	v_mov_b32_dpp v77, v76 quad_perm:[1,0,3,2] row_mask:0xf bank_mask:0xf bound_ctrl:1
	v_pk_mul_f32 v[72:73], v[36:37], v[30:31] op_sel_hi:[1,0]
	v_pk_mul_f32 v[74:75], v[36:37], v[30:31] op_sel:[0,1] op_sel_hi:[1,1]
	v_pk_fma_f32 v[68:69], v[2:3], v[24:25], v[68:69] op_sel_hi:[1,0,1]
	v_pk_fma_f32 v[70:71], v[4:5], v[24:25], v[70:71] op_sel:[0,1,0] op_sel_hi:[1,1,1]
	v_pk_fma_f32 v[72:73], v[6:7], v[26:27], v[72:73] op_sel_hi:[1,0,1]
	v_pk_fma_f32 v[74:75], v[8:9], v[26:27], v[74:75] op_sel:[0,1,0] op_sel_hi:[1,1,1]
	v_pk_fma_f32 v[2:3], v[32:33], v[76:77], v[68:69] op_sel_hi:[0,1,1] neg_lo:[1,0,0] neg_hi:[1,0,0]
	v_pk_fma_f32 v[4:5], v[32:33], v[76:77], v[70:71] op_sel:[1,0,0] op_sel_hi:[1,1,1] neg_lo:[1,0,0] neg_hi:[1,0,0]
	v_add_f32_dpp v81, v67, v66 quad_perm:[1,0,3,2] row_mask:0xf bank_mask:0xf bound_ctrl:1
	v_pk_fma_f32 v[6:7], v[34:35], v[76:77], v[72:73] op_sel_hi:[0,1,1] neg_lo:[1,0,0] neg_hi:[1,0,0]
	v_pk_fma_f32 v[8:9], v[34:35], v[76:77], v[74:75] op_sel:[1,0,0] op_sel_hi:[1,1,1] neg_lo:[1,0,0] neg_hi:[1,0,0]
	v_add_f32_dpp v82, v81, v81 quad_perm:[3,2,1,0] row_mask:0xf bank_mask:0xf bound_ctrl:1
	v_fma_f32 v83, v36, v90, v82
	v_fma_f32 v82, -v76, v91, v83
	ds_write_b32 v14, v82 offset:8192
	s_waitcnt lgkmcnt(1)
; #define LAS __attribute__((address_space(3)))
; template <int CTRL> __device__ __forceinline__ float dppf(float x) { return __builtin_bit_cast(float, __builtin_amdgcn_mov_dpp(__builtin_bit_cast(int, x), CTRL, 0xf, 0xf, true)); }
; __device__ __forceinline__ float sum16(float x) { x = sum8(x); x += dppf<0x140>(x); return x; }
; __device__ __forceinline__ void rwkv_item(LAS unsigned char* lds, int l, const bf16_t* PROJ, const bf16_t* LO, bf16_t* YR, float* BON, int b, int h, int qv) {
;     ...
;             for (int t = 0; t < CH; ++t) {
;                 const int tn = (t + 1) & (CH - 1);
;                 const LAS float* pn = pk + tn * 64;
;                 const f32x4 nkk = *(const LAS f32x4*)(pn), nwr = *(const LAS f32x4*)(pn + 2048), nw = *(const LAS f32x4*)(pn + 4096), nk = *(const LAS f32x4*)(pn + 6144), na = *(const LAS f32x4*)(pn + 8192);
;                 const float nv0 = pv[tn * 32], nv1 = pv[tn * 32 + 4]; const f32x2 nsc = *(const LAS f32x2*)(ps + 2 * tn);
;                 float sa[2], yp[2];
; #pragma unroll
;                 for (int c = 0; c < 2; ++c) { const f32x2 pa = S23[c] * kk4.hi + S01[c] * kk4.lo, pb = S23[c] * wr4.hi + S01[c] * wr4.lo; sa[c] = pa.x + pa.y; yp[c] = pb.x + pb.y; }
; #pragma unroll
;                 for (int c = 0; c < 2; ++c) { sa[c] = sum16(sa[c]); yp[c] += dppf<0xB1>(yp[c]); yp[c] += dppf<0x4E>(yp[c]); }
; #pragma unroll
;                 for (int c = 0; c < 2; ++c) {
;                     S01[c] = S01[c] * w4.lo + (k4.lo * vv[c] - a4.lo * sa[c]);
;                     S23[c] = S23[c] * w4.hi + (k4.hi * vv[c] - a4.hi * sa[c]);
;                     py[(t * 32 + 4 * c) * 4] = yp[c] + 0.25f * (vv[c] * sc.x - sa[c] * sc.y);
;                 }
;                 kk4 = nkk; wr4 = nwr; w4 = nw; k4 = nk; a4 = na; vv[0] = nv0; vv[1] = nv1; sc = nsc;
;             }
	v_pk_mul_f32 v[64:65], v[2:3], v[40:41] op_sel_hi:[1,0]
	v_pk_mul_f32 v[66:67], v[2:3], v[44:45] op_sel_hi:[1,0]
	v_pk_fma_f32 v[64:65], v[4:5], v[40:41], v[64:65] op_sel:[0,1,0] op_sel_hi:[1,1,1]
	v_pk_fma_f32 v[66:67], v[4:5], v[44:45], v[66:67] op_sel:[0,1,0] op_sel_hi:[1,1,1]
	v_pk_fma_f32 v[64:65], v[6:7], v[42:43], v[64:65] op_sel_hi:[1,0,1]
	v_pk_fma_f32 v[66:67], v[6:7], v[46:47], v[66:67] op_sel_hi:[1,0,1]
	v_pk_fma_f32 v[64:65], v[8:9], v[42:43], v[64:65] op_sel:[0,1,0] op_sel_hi:[1,1,1]
	v_pk_fma_f32 v[66:67], v[8:9], v[46:47], v[66:67] op_sel:[0,1,0] op_sel_hi:[1,1,1]
	ds_read_b128 v[16:19], v10 offset:4608
	v_add_f32_dpp v78, v65, v64 quad_perm:[1,0,3,2] row_mask:0xf bank_mask:0xf bound_ctrl:1
	ds_read_b128 v[20:23], v10 offset:12800
	ds_read_b128 v[24:27], v10 offset:20992
	v_add_f32_dpp v79, v78, v78 quad_perm:[3,2,1,0] row_mask:0xf bank_mask:0xf bound_ctrl:1
	ds_read_b128 v[28:31], v10 offset:29184
	ds_read_b128 v[32:35], v10 offset:37376
	v_add_f32_dpp v80, v79, v79 row_half_mirror row_mask:0xf bank_mask:0xf bound_ctrl:1
	ds_read_b32 v36, v11 offset:43264
	ds_read_b32 v37, v12 offset:43264
	v_add_f32_dpp v76, v80, v80 row_mirror row_mask:0xf bank_mask:0xf bound_ctrl:1
	v_pk_mul_f32 v[68:69], v[60:61], v[52:53] op_sel_hi:[1,0]
	v_pk_mul_f32 v[70:71], v[60:61], v[52:53] op_sel:[0,1] op_sel_hi:[1,1]
	v_mov_b32_dpp v77, v76 quad_perm:[1,0,3,2] row_mask:0xf bank_mask:0xf bound_ctrl:1
	v_pk_mul_f32 v[72:73], v[60:61], v[54:55] op_sel_hi:[1,0]
	v_pk_mul_f32 v[74:75], v[60:61], v[54:55] op_sel:[0,1] op_sel_hi:[1,1]
	v_pk_fma_f32 v[68:69], v[2:3], v[48:49], v[68:69] op_sel_hi:[1,0,1]
	v_pk_fma_f32 v[70:71], v[4:5], v[48:49], v[70:71] op_sel:[0,1,0] op_sel_hi:[1,1,1]
	v_pk_fma_f32 v[72:73], v[6:7], v[50:51], v[72:73] op_sel_hi:[1,0,1]
	v_pk_fma_f32 v[74:75], v[8:9], v[50:51], v[74:75] op_sel:[0,1,0] op_sel_hi:[1,1,1]
	v_pk_fma_f32 v[2:3], v[56:57], v[76:77], v[68:69] op_sel_hi:[0,1,1] neg_lo:[1,0,0] neg_hi:[1,0,0]
	v_pk_fma_f32 v[4:5], v[56:57], v[76:77], v[70:71] op_sel:[1,0,0] op_sel_hi:[1,1,1] neg_lo:[1,0,0] neg_hi:[1,0,0]
	v_add_f32_dpp v81, v67, v66 quad_perm:[1,0,3,2] row_mask:0xf bank_mask:0xf bound_ctrl:1
	v_pk_fma_f32 v[6:7], v[58:59], v[76:77], v[72:73] op_sel_hi:[0,1,1] neg_lo:[1,0,0] neg_hi:[1,0,0]
	v_pk_fma_f32 v[8:9], v[58:59], v[76:77], v[74:75] op_sel:[1,0,0] op_sel_hi:[1,1,1] neg_lo:[1,0,0] neg_hi:[1,0,0]
	v_add_f32_dpp v82, v81, v81 quad_perm:[3,2,1,0] row_mask:0xf bank_mask:0xf bound_ctrl:1
	v_fma_f32 v83, v60, v92, v82
	v_fma_f32 v82, -v76, v93, v83
	ds_write_b32 v14, v82 offset:8704
	s_waitcnt lgkmcnt(1)
	v_pk_mul_f32 v[64:65], v[2:3], v[16:17] op_sel_hi:[1,0]
	v_pk_mul_f32 v[66:67], v[2:3], v[20:21] op_sel_hi:[1,0]
	v_pk_fma_f32 v[64:65], v[4:5], v[16:17], v[64:65] op_sel:[0,1,0] op_sel_hi:[1,1,1]
	v_pk_fma_f32 v[66:67], v[4:5], v[20:21], v[66:67] op_sel:[0,1,0] op_sel_hi:[1,1,1]
	v_pk_fma_f32 v[64:65], v[6:7], v[18:19], v[64:65] op_sel_hi:[1,0,1]
	v_pk_fma_f32 v[66:67], v[6:7], v[22:23], v[66:67] op_sel_hi:[1,0,1]
	v_pk_fma_f32 v[64:65], v[8:9], v[18:19], v[64:65] op_sel:[0,1,0] op_sel_hi:[1,1,1]
	v_pk_fma_f32 v[66:67], v[8:9], v[22:23], v[66:67] op_sel:[0,1,0] op_sel_hi:[1,1,1]
	ds_read_b128 v[40:43], v10 offset:4864
	v_add_f32_dpp v78, v65, v64 quad_perm:[1,0,3,2] row_mask:0xf bank_mask:0xf bound_ctrl:1
	ds_read_b128 v[44:47], v10 offset:13056
	ds_read_b128 v[48:51], v10 offset:21248
	v_add_f32_dpp v79, v78, v78 quad_perm:[3,2,1,0] row_mask:0xf bank_mask:0xf bound_ctrl:1
	ds_read_b128 v[52:55], v10 offset:29440
	ds_read_b128 v[56:59], v10 offset:37632
	v_add_f32_dpp v80, v79, v79 row_half_mirror row_mask:0xf bank_mask:0xf bound_ctrl:1
	ds_read_b32 v60, v11 offset:43392
	ds_read_b32 v61, v12 offset:43392
	v_add_f32_dpp v76, v80, v80 row_mirror row_mask:0xf bank_mask:0xf bound_ctrl:1
	ds_read_b128 v[90:93], v100 offset:160
	v_pk_mul_f32 v[68:69], v[36:37], v[28:29] op_sel_hi:[1,0]
	v_pk_mul_f32 v[70:71], v[36:37], v[28:29] op_sel:[0,1] op_sel_hi:[1,1]
	v_mov_b32_dpp v77, v76 quad_perm:[1,0,3,2] row_mask:0xf bank_mask:0xf bound_ctrl:1
	v_pk_mul_f32 v[72:73], v[36:37], v[30:31] op_sel_hi:[1,0]
	v_pk_mul_f32 v[74:75], v[36:37], v[30:31] op_sel:[0,1] op_sel_hi:[1,1]
	v_pk_fma_f32 v[68:69], v[2:3], v[24:25], v[68:69] op_sel_hi:[1,0,1]
	v_pk_fma_f32 v[70:71], v[4:5], v[24:25], v[70:71] op_sel:[0,1,0] op_sel_hi:[1,1,1]
	v_pk_fma_f32 v[72:73], v[6:7], v[26:27], v[72:73] op_sel_hi:[1,0,1]
	v_pk_fma_f32 v[74:75], v[8:9], v[26:27], v[74:75] op_sel:[0,1,0] op_sel_hi:[1,1,1]
	v_pk_fma_f32 v[2:3], v[32:33], v[76:77], v[68:69] op_sel_hi:[0,1,1] neg_lo:[1,0,0] neg_hi:[1,0,0]
	v_pk_fma_f32 v[4:5], v[32:33], v[76:77], v[70:71] op_sel:[1,0,0] op_sel_hi:[1,1,1] neg_lo:[1,0,0] neg_hi:[1,0,0]
	v_add_f32_dpp v81, v67, v66 quad_perm:[1,0,3,2] row_mask:0xf bank_mask:0xf bound_ctrl:1
	v_pk_fma_f32 v[6:7], v[34:35], v[76:77], v[72:73] op_sel_hi:[0,1,1] neg_lo:[1,0,0] neg_hi:[1,0,0]
	v_pk_fma_f32 v[8:9], v[34:35], v[76:77], v[74:75] op_sel:[1,0,0] op_sel_hi:[1,1,1] neg_lo:[1,0,0] neg_hi:[1,0,0]
	v_add_f32_dpp v82, v81, v81 quad_perm:[3,2,1,0] row_mask:0xf bank_mask:0xf bound_ctrl:1
	v_fma_f32 v83, v36, v94, v82
	v_fma_f32 v82, -v76, v95, v83
	ds_write_b32 v14, v82 offset:9216
	s_waitcnt lgkmcnt(1)
; #define LAS __attribute__((address_space(3)))
; template <int CTRL> __device__ __forceinline__ float dppf(float x) { return __builtin_bit_cast(float, __builtin_amdgcn_mov_dpp(__builtin_bit_cast(int, x), CTRL, 0xf, 0xf, true)); }
; __device__ __forceinline__ float sum16(float x) { x = sum8(x); x += dppf<0x140>(x); return x; }
; __device__ __forceinline__ void rwkv_item(LAS unsigned char* lds, int l, const bf16_t* PROJ, const bf16_t* LO, bf16_t* YR, float* BON, int b, int h, int qv) {
;     ...
;             for (int t = 0; t < CH; ++t) {
;                 const int tn = (t + 1) & (CH - 1);
;                 const LAS float* pn = pk + tn * 64;
;                 const f32x4 nkk = *(const LAS f32x4*)(pn), nwr = *(const LAS f32x4*)(pn + 2048), nw = *(const LAS f32x4*)(pn + 4096), nk = *(const LAS f32x4*)(pn + 6144), na = *(const LAS f32x4*)(pn + 8192);
;                 const float nv0 = pv[tn * 32], nv1 = pv[tn * 32 + 4]; const f32x2 nsc = *(const LAS f32x2*)(ps + 2 * tn);
;                 float sa[2], yp[2];
; #pragma unroll
;                 for (int c = 0; c < 2; ++c) { const f32x2 pa = S23[c] * kk4.hi + S01[c] * kk4.lo, pb = S23[c] * wr4.hi + S01[c] * wr4.lo; sa[c] = pa.x + pa.y; yp[c] = pb.x + pb.y; }
; #pragma unroll
;                 for (int c = 0; c < 2; ++c) { sa[c] = sum16(sa[c]); yp[c] += dppf<0xB1>(yp[c]); yp[c] += dppf<0x4E>(yp[c]); }
; #pragma unroll
;                 for (int c = 0; c < 2; ++c) {
;                     S01[c] = S01[c] * w4.lo + (k4.lo * vv[c] - a4.lo * sa[c]);
;                     S23[c] = S23[c] * w4.hi + (k4.hi * vv[c] - a4.hi * sa[c]);
;                     py[(t * 32 + 4 * c) * 4] = yp[c] + 0.25f * (vv[c] * sc.x - sa[c] * sc.y);
;                 }
;                 kk4 = nkk; wr4 = nwr; w4 = nw; k4 = nk; a4 = na; vv[0] = nv0; vv[1] = nv1; sc = nsc;
;             }
	v_pk_mul_f32 v[64:65], v[2:3], v[40:41] op_sel_hi:[1,0]
	v_pk_mul_f32 v[66:67], v[2:3], v[44:45] op_sel_hi:[1,0]
	v_pk_fma_f32 v[64:65], v[4:5], v[40:41], v[64:65] op_sel:[0,1,0] op_sel_hi:[1,1,1]
	v_pk_fma_f32 v[66:67], v[4:5], v[44:45], v[66:67] op_sel:[0,1,0] op_sel_hi:[1,1,1]
	v_pk_fma_f32 v[64:65], v[6:7], v[42:43], v[64:65] op_sel_hi:[1,0,1]
	v_pk_fma_f32 v[66:67], v[6:7], v[46:47], v[66:67] op_sel_hi:[1,0,1]
	v_pk_fma_f32 v[64:65], v[8:9], v[42:43], v[64:65] op_sel:[0,1,0] op_sel_hi:[1,1,1]
	v_pk_fma_f32 v[66:67], v[8:9], v[46:47], v[66:67] op_sel:[0,1,0] op_sel_hi:[1,1,1]
	ds_read_b128 v[16:19], v10 offset:5120
	v_add_f32_dpp v78, v65, v64 quad_perm:[1,0,3,2] row_mask:0xf bank_mask:0xf bound_ctrl:1
	ds_read_b128 v[20:23], v10 offset:13312
	ds_read_b128 v[24:27], v10 offset:21504
	v_add_f32_dpp v79, v78, v78 quad_perm:[3,2,1,0] row_mask:0xf bank_mask:0xf bound_ctrl:1
	ds_read_b128 v[28:31], v10 offset:29696
	ds_read_b128 v[32:35], v10 offset:37888
	v_add_f32_dpp v80, v79, v79 row_half_mirror row_mask:0xf bank_mask:0xf bound_ctrl:1
	ds_read_b32 v36, v11 offset:43520
	ds_read_b32 v37, v12 offset:43520
	v_add_f32_dpp v76, v80, v80 row_mirror row_mask:0xf bank_mask:0xf bound_ctrl:1
	v_pk_mul_f32 v[68:69], v[60:61], v[52:53] op_sel_hi:[1,0]
	v_pk_mul_f32 v[70:71], v[60:61], v[52:53] op_sel:[0,1] op_sel_hi:[1,1]
	v_mov_b32_dpp v77, v76 quad_perm:[1,0,3,2] row_mask:0xf bank_mask:0xf bound_ctrl:1
	v_pk_mul_f32 v[72:73], v[60:61], v[54:55] op_sel_hi:[1,0]
	v_pk_mul_f32 v[74:75], v[60:61], v[54:55] op_sel:[0,1] op_sel_hi:[1,1]
	v_pk_fma_f32 v[68:69], v[2:3], v[48:49], v[68:69] op_sel_hi:[1,0,1]
	v_pk_fma_f32 v[70:71], v[4:5], v[48:49], v[70:71] op_sel:[0,1,0] op_sel_hi:[1,1,1]
	v_pk_fma_f32 v[72:73], v[6:7], v[50:51], v[72:73] op_sel_hi:[1,0,1]
	v_pk_fma_f32 v[74:75], v[8:9], v[50:51], v[74:75] op_sel:[0,1,0] op_sel_hi:[1,1,1]
	v_pk_fma_f32 v[2:3], v[56:57], v[76:77], v[68:69] op_sel_hi:[0,1,1] neg_lo:[1,0,0] neg_hi:[1,0,0]
	v_pk_fma_f32 v[4:5], v[56:57], v[76:77], v[70:71] op_sel:[1,0,0] op_sel_hi:[1,1,1] neg_lo:[1,0,0] neg_hi:[1,0,0]
	v_add_f32_dpp v81, v67, v66 quad_perm:[1,0,3,2] row_mask:0xf bank_mask:0xf bound_ctrl:1
	v_pk_fma_f32 v[6:7], v[58:59], v[76:77], v[72:73] op_sel_hi:[0,1,1] neg_lo:[1,0,0] neg_hi:[1,0,0]
	v_pk_fma_f32 v[8:9], v[58:59], v[76:77], v[74:75] op_sel:[1,0,0] op_sel_hi:[1,1,1] neg_lo:[1,0,0] neg_hi:[1,0,0]
	v_add_f32_dpp v82, v81, v81 quad_perm:[3,2,1,0] row_mask:0xf bank_mask:0xf bound_ctrl:1
	v_fma_f32 v83, v60, v96, v82
	v_fma_f32 v82, -v76, v97, v83
	ds_write_b32 v14, v82 offset:9728
	s_waitcnt lgkmcnt(1)
	v_pk_mul_f32 v[64:65], v[2:3], v[16:17] op_sel_hi:[1,0]
	v_pk_mul_f32 v[66:67], v[2:3], v[20:21] op_sel_hi:[1,0]
	v_pk_fma_f32 v[64:65], v[4:5], v[16:17], v[64:65] op_sel:[0,1,0] op_sel_hi:[1,1,1]
	v_pk_fma_f32 v[66:67], v[4:5], v[20:21], v[66:67] op_sel:[0,1,0] op_sel_hi:[1,1,1]
	v_pk_fma_f32 v[64:65], v[6:7], v[18:19], v[64:65] op_sel_hi:[1,0,1]
	v_pk_fma_f32 v[66:67], v[6:7], v[22:23], v[66:67] op_sel_hi:[1,0,1]
	v_pk_fma_f32 v[64:65], v[8:9], v[18:19], v[64:65] op_sel:[0,1,0] op_sel_hi:[1,1,1]
	v_pk_fma_f32 v[66:67], v[8:9], v[22:23], v[66:67] op_sel:[0,1,0] op_sel_hi:[1,1,1]
	ds_read_b128 v[40:43], v10 offset:5376
	v_add_f32_dpp v78, v65, v64 quad_perm:[1,0,3,2] row_mask:0xf bank_mask:0xf bound_ctrl:1
	ds_read_b128 v[44:47], v10 offset:13568
	ds_read_b128 v[48:51], v10 offset:21760
	v_add_f32_dpp v79, v78, v78 quad_perm:[3,2,1,0] row_mask:0xf bank_mask:0xf bound_ctrl:1
	ds_read_b128 v[52:55], v10 offset:29952
	ds_read_b128 v[56:59], v10 offset:38144
	v_add_f32_dpp v80, v79, v79 row_half_mirror row_mask:0xf bank_mask:0xf bound_ctrl:1
	ds_read_b32 v60, v11 offset:43648
	ds_read_b32 v61, v12 offset:43648
	v_add_f32_dpp v76, v80, v80 row_mirror row_mask:0xf bank_mask:0xf bound_ctrl:1
	ds_read_b128 v[94:97], v100 offset:176
	v_pk_mul_f32 v[68:69], v[36:37], v[28:29] op_sel_hi:[1,0]
	v_pk_mul_f32 v[70:71], v[36:37], v[28:29] op_sel:[0,1] op_sel_hi:[1,1]
	v_mov_b32_dpp v77, v76 quad_perm:[1,0,3,2] row_mask:0xf bank_mask:0xf bound_ctrl:1
	v_pk_mul_f32 v[72:73], v[36:37], v[30:31] op_sel_hi:[1,0]
	v_pk_mul_f32 v[74:75], v[36:37], v[30:31] op_sel:[0,1] op_sel_hi:[1,1]
	v_pk_fma_f32 v[68:69], v[2:3], v[24:25], v[68:69] op_sel_hi:[1,0,1]
	v_pk_fma_f32 v[70:71], v[4:5], v[24:25], v[70:71] op_sel:[0,1,0] op_sel_hi:[1,1,1]
	v_pk_fma_f32 v[72:73], v[6:7], v[26:27], v[72:73] op_sel_hi:[1,0,1]
	v_pk_fma_f32 v[74:75], v[8:9], v[26:27], v[74:75] op_sel:[0,1,0] op_sel_hi:[1,1,1]
	v_pk_fma_f32 v[2:3], v[32:33], v[76:77], v[68:69] op_sel_hi:[0,1,1] neg_lo:[1,0,0] neg_hi:[1,0,0]
	v_pk_fma_f32 v[4:5], v[32:33], v[76:77], v[70:71] op_sel:[1,0,0] op_sel_hi:[1,1,1] neg_lo:[1,0,0] neg_hi:[1,0,0]
	v_add_f32_dpp v81, v67, v66 quad_perm:[1,0,3,2] row_mask:0xf bank_mask:0xf bound_ctrl:1
	v_pk_fma_f32 v[6:7], v[34:35], v[76:77], v[72:73] op_sel_hi:[0,1,1] neg_lo:[1,0,0] neg_hi:[1,0,0]
	v_pk_fma_f32 v[8:9], v[34:35], v[76:77], v[74:75] op_sel:[1,0,0] op_sel_hi:[1,1,1] neg_lo:[1,0,0] neg_hi:[1,0,0]
	v_add_f32_dpp v82, v81, v81 quad_perm:[3,2,1,0] row_mask:0xf bank_mask:0xf bound_ctrl:1
	v_fma_f32 v83, v36, v90, v82
	v_fma_f32 v82, -v76, v91, v83
	ds_write_b32 v14, v82 offset:10240
	s_waitcnt lgkmcnt(1)
; #define LAS __attribute__((address_space(3)))
; template <int CTRL> __device__ __forceinline__ float dppf(float x) { return __builtin_bit_cast(float, __builtin_amdgcn_mov_dpp(__builtin_bit_cast(int, x), CTRL, 0xf, 0xf, true)); }
; __device__ __forceinline__ float sum16(float x) { x = sum8(x); x += dppf<0x140>(x); return x; }
; __device__ __forceinline__ void rwkv_item(LAS unsigned char* lds, int l, const bf16_t* PROJ, const bf16_t* LO, bf16_t* YR, float* BON, int b, int h, int qv) {
;     ...
;             for (int t = 0; t < CH; ++t) {
;                 const int tn = (t + 1) & (CH - 1);
;                 const LAS float* pn = pk + tn * 64;
;                 const f32x4 nkk = *(const LAS f32x4*)(pn), nwr = *(const LAS f32x4*)(pn + 2048), nw = *(const LAS f32x4*)(pn + 4096), nk = *(const LAS f32x4*)(pn + 6144), na = *(const LAS f32x4*)(pn + 8192);
;                 const float nv0 = pv[tn * 32], nv1 = pv[tn * 32 + 4]; const f32x2 nsc = *(const LAS f32x2*)(ps + 2 * tn);
;                 float sa[2], yp[2];
; #pragma unroll
;                 for (int c = 0; c < 2; ++c) { const f32x2 pa = S23[c] * kk4.hi + S01[c] * kk4.lo, pb = S23[c] * wr4.hi + S01[c] * wr4.lo; sa[c] = pa.x + pa.y; yp[c] = pb.x + pb.y; }
; #pragma unroll
;                 for (int c = 0; c < 2; ++c) { sa[c] = sum16(sa[c]); yp[c] += dppf<0xB1>(yp[c]); yp[c] += dppf<0x4E>(yp[c]); }
; #pragma unroll
;                 for (int c = 0; c < 2; ++c) {
;                     S01[c] = S01[c] * w4.lo + (k4.lo * vv[c] - a4.lo * sa[c]);
;                     S23[c] = S23[c] * w4.hi + (k4.hi * vv[c] - a4.hi * sa[c]);
;                     py[(t * 32 + 4 * c) * 4] = yp[c] + 0.25f * (vv[c] * sc.x - sa[c] * sc.y);
;                 }
;                 kk4 = nkk; wr4 = nwr; w4 = nw; k4 = nk; a4 = na; vv[0] = nv0; vv[1] = nv1; sc = nsc;
;             }
	v_pk_mul_f32 v[64:65], v[2:3], v[40:41] op_sel_hi:[1,0]
	v_pk_mul_f32 v[66:67], v[2:3], v[44:45] op_sel_hi:[1,0]
	v_pk_fma_f32 v[64:65], v[4:5], v[40:41], v[64:65] op_sel:[0,1,0] op_sel_hi:[1,1,1]
	v_pk_fma_f32 v[66:67], v[4:5], v[44:45], v[66:67] op_sel:[0,1,0] op_sel_hi:[1,1,1]
	v_pk_fma_f32 v[64:65], v[6:7], v[42:43], v[64:65] op_sel_hi:[1,0,1]
	v_pk_fma_f32 v[66:67], v[6:7], v[46:47], v[66:67] op_sel_hi:[1,0,1]
	v_pk_fma_f32 v[64:65], v[8:9], v[42:43], v[64:65] op_sel:[0,1,0] op_sel_hi:[1,1,1]
	v_pk_fma_f32 v[66:67], v[8:9], v[46:47], v[66:67] op_sel:[0,1,0] op_sel_hi:[1,1,1]
	ds_read_b128 v[16:19], v10 offset:5632
	v_add_f32_dpp v78, v65, v64 quad_perm:[1,0,3,2] row_mask:0xf bank_mask:0xf bound_ctrl:1
	ds_read_b128 v[20:23], v10 offset:13824
	ds_read_b128 v[24:27], v10 offset:22016
	v_add_f32_dpp v79, v78, v78 quad_perm:[3,2,1,0] row_mask:0xf bank_mask:0xf bound_ctrl:1
	ds_read_b128 v[28:31], v10 offset:30208
	ds_read_b128 v[32:35], v10 offset:38400
	v_add_f32_dpp v80, v79, v79 row_half_mirror row_mask:0xf bank_mask:0xf bound_ctrl:1
	ds_read_b32 v36, v11 offset:43776
	ds_read_b32 v37, v12 offset:43776
	v_add_f32_dpp v76, v80, v80 row_mirror row_mask:0xf bank_mask:0xf bound_ctrl:1
	v_pk_mul_f32 v[68:69], v[60:61], v[52:53] op_sel_hi:[1,0]
	v_pk_mul_f32 v[70:71], v[60:61], v[52:53] op_sel:[0,1] op_sel_hi:[1,1]
	v_mov_b32_dpp v77, v76 quad_perm:[1,0,3,2] row_mask:0xf bank_mask:0xf bound_ctrl:1
	v_pk_mul_f32 v[72:73], v[60:61], v[54:55] op_sel_hi:[1,0]
	v_pk_mul_f32 v[74:75], v[60:61], v[54:55] op_sel:[0,1] op_sel_hi:[1,1]
	v_pk_fma_f32 v[68:69], v[2:3], v[48:49], v[68:69] op_sel_hi:[1,0,1]
	v_pk_fma_f32 v[70:71], v[4:5], v[48:49], v[70:71] op_sel:[0,1,0] op_sel_hi:[1,1,1]
	v_pk_fma_f32 v[72:73], v[6:7], v[50:51], v[72:73] op_sel_hi:[1,0,1]
	v_pk_fma_f32 v[74:75], v[8:9], v[50:51], v[74:75] op_sel:[0,1,0] op_sel_hi:[1,1,1]
	v_pk_fma_f32 v[2:3], v[56:57], v[76:77], v[68:69] op_sel_hi:[0,1,1] neg_lo:[1,0,0] neg_hi:[1,0,0]
	v_pk_fma_f32 v[4:5], v[56:57], v[76:77], v[70:71] op_sel:[1,0,0] op_sel_hi:[1,1,1] neg_lo:[1,0,0] neg_hi:[1,0,0]
	v_add_f32_dpp v81, v67, v66 quad_perm:[1,0,3,2] row_mask:0xf bank_mask:0xf bound_ctrl:1
	v_pk_fma_f32 v[6:7], v[58:59], v[76:77], v[72:73] op_sel_hi:[0,1,1] neg_lo:[1,0,0] neg_hi:[1,0,0]
	v_pk_fma_f32 v[8:9], v[58:59], v[76:77], v[74:75] op_sel:[1,0,0] op_sel_hi:[1,1,1] neg_lo:[1,0,0] neg_hi:[1,0,0]
	v_add_f32_dpp v82, v81, v81 quad_perm:[3,2,1,0] row_mask:0xf bank_mask:0xf bound_ctrl:1
	v_fma_f32 v83, v60, v92, v82
	v_fma_f32 v82, -v76, v93, v83
	ds_write_b32 v14, v82 offset:10752
	s_waitcnt lgkmcnt(1)
	v_pk_mul_f32 v[64:65], v[2:3], v[16:17] op_sel_hi:[1,0]
	v_pk_mul_f32 v[66:67], v[2:3], v[20:21] op_sel_hi:[1,0]
	v_pk_fma_f32 v[64:65], v[4:5], v[16:17], v[64:65] op_sel:[0,1,0] op_sel_hi:[1,1,1]
	v_pk_fma_f32 v[66:67], v[4:5], v[20:21], v[66:67] op_sel:[0,1,0] op_sel_hi:[1,1,1]
	v_pk_fma_f32 v[64:65], v[6:7], v[18:19], v[64:65] op_sel_hi:[1,0,1]
	v_pk_fma_f32 v[66:67], v[6:7], v[22:23], v[66:67] op_sel_hi:[1,0,1]
	v_pk_fma_f32 v[64:65], v[8:9], v[18:19], v[64:65] op_sel:[0,1,0] op_sel_hi:[1,1,1]
	v_pk_fma_f32 v[66:67], v[8:9], v[22:23], v[66:67] op_sel:[0,1,0] op_sel_hi:[1,1,1]
	ds_read_b128 v[40:43], v10 offset:5888
	v_add_f32_dpp v78, v65, v64 quad_perm:[1,0,3,2] row_mask:0xf bank_mask:0xf bound_ctrl:1
	ds_read_b128 v[44:47], v10 offset:14080
	ds_read_b128 v[48:51], v10 offset:22272
	v_add_f32_dpp v79, v78, v78 quad_perm:[3,2,1,0] row_mask:0xf bank_mask:0xf bound_ctrl:1
	ds_read_b128 v[52:55], v10 offset:30464
	ds_read_b128 v[56:59], v10 offset:38656
	v_add_f32_dpp v80, v79, v79 row_half_mirror row_mask:0xf bank_mask:0xf bound_ctrl:1
	ds_read_b32 v60, v11 offset:43904
	ds_read_b32 v61, v12 offset:43904
	v_add_f32_dpp v76, v80, v80 row_mirror row_mask:0xf bank_mask:0xf bound_ctrl:1
	ds_read_b128 v[90:93], v100 offset:192
	v_pk_mul_f32 v[68:69], v[36:37], v[28:29] op_sel_hi:[1,0]
	v_pk_mul_f32 v[70:71], v[36:37], v[28:29] op_sel:[0,1] op_sel_hi:[1,1]
	v_mov_b32_dpp v77, v76 quad_perm:[1,0,3,2] row_mask:0xf bank_mask:0xf bound_ctrl:1
	v_pk_mul_f32 v[72:73], v[36:37], v[30:31] op_sel_hi:[1,0]
	v_pk_mul_f32 v[74:75], v[36:37], v[30:31] op_sel:[0,1] op_sel_hi:[1,1]
	v_pk_fma_f32 v[68:69], v[2:3], v[24:25], v[68:69] op_sel_hi:[1,0,1]
	v_pk_fma_f32 v[70:71], v[4:5], v[24:25], v[70:71] op_sel:[0,1,0] op_sel_hi:[1,1,1]
	v_pk_fma_f32 v[72:73], v[6:7], v[26:27], v[72:73] op_sel_hi:[1,0,1]
	v_pk_fma_f32 v[74:75], v[8:9], v[26:27], v[74:75] op_sel:[0,1,0] op_sel_hi:[1,1,1]
	v_pk_fma_f32 v[2:3], v[32:33], v[76:77], v[68:69] op_sel_hi:[0,1,1] neg_lo:[1,0,0] neg_hi:[1,0,0]
	v_pk_fma_f32 v[4:5], v[32:33], v[76:77], v[70:71] op_sel:[1,0,0] op_sel_hi:[1,1,1] neg_lo:[1,0,0] neg_hi:[1,0,0]
	v_add_f32_dpp v81, v67, v66 quad_perm:[1,0,3,2] row_mask:0xf bank_mask:0xf bound_ctrl:1
	v_pk_fma_f32 v[6:7], v[34:35], v[76:77], v[72:73] op_sel_hi:[0,1,1] neg_lo:[1,0,0] neg_hi:[1,0,0]
	v_pk_fma_f32 v[8:9], v[34:35], v[76:77], v[74:75] op_sel:[1,0,0] op_sel_hi:[1,1,1] neg_lo:[1,0,0] neg_hi:[1,0,0]
	v_add_f32_dpp v82, v81, v81 quad_perm:[3,2,1,0] row_mask:0xf bank_mask:0xf bound_ctrl:1
	v_fma_f32 v83, v36, v94, v82
	v_fma_f32 v82, -v76, v95, v83
	ds_write_b32 v14, v82 offset:11264
	s_waitcnt lgkmcnt(1)
; #define LAS __attribute__((address_space(3)))
; template <int CTRL> __device__ __forceinline__ float dppf(float x) { return __builtin_bit_cast(float, __builtin_amdgcn_mov_dpp(__builtin_bit_cast(int, x), CTRL, 0xf, 0xf, true)); }
; __device__ __forceinline__ float sum16(float x) { x = sum8(x); x += dppf<0x140>(x); return x; }
; __device__ __forceinline__ void rwkv_item(LAS unsigned char* lds, int l, const bf16_t* PROJ, const bf16_t* LO, bf16_t* YR, float* BON, int b, int h, int qv) {
;     ...
;             for (int t = 0; t < CH; ++t) {
;                 const int tn = (t + 1) & (CH - 1);
;                 const LAS float* pn = pk + tn * 64;
;                 const f32x4 nkk = *(const LAS f32x4*)(pn), nwr = *(const LAS f32x4*)(pn + 2048), nw = *(const LAS f32x4*)(pn + 4096), nk = *(const LAS f32x4*)(pn + 6144), na = *(const LAS f32x4*)(pn + 8192);
;                 const float nv0 = pv[tn * 32], nv1 = pv[tn * 32 + 4]; const f32x2 nsc = *(const LAS f32x2*)(ps + 2 * tn);
;                 float sa[2], yp[2];
; #pragma unroll
;                 for (int c = 0; c < 2; ++c) { const f32x2 pa = S23[c] * kk4.hi + S01[c] * kk4.lo, pb = S23[c] * wr4.hi + S01[c] * wr4.lo; sa[c] = pa.x + pa.y; yp[c] = pb.x + pb.y; }
; #pragma unroll
;                 for (int c = 0; c < 2; ++c) { sa[c] = sum16(sa[c]); yp[c] += dppf<0xB1>(yp[c]); yp[c] += dppf<0x4E>(yp[c]); }
; #pragma unroll
;                 for (int c = 0; c < 2; ++c) {
;                     S01[c] = S01[c] * w4.lo + (k4.lo * vv[c] - a4.lo * sa[c]);
;                     S23[c] = S23[c] * w4.hi + (k4.hi * vv[c] - a4.hi * sa[c]);
;                     py[(t * 32 + 4 * c) * 4] = yp[c] + 0.25f * (vv[c] * sc.x - sa[c] * sc.y);
;                 }
;                 kk4 = nkk; wr4 = nwr; w4 = nw; k4 = nk; a4 = na; vv[0] = nv0; vv[1] = nv1; sc = nsc;
;             }
	v_pk_mul_f32 v[64:65], v[2:3], v[40:41] op_sel_hi:[1,0]
	v_pk_mul_f32 v[66:67], v[2:3], v[44:45] op_sel_hi:[1,0]
	v_pk_fma_f32 v[64:65], v[4:5], v[40:41], v[64:65] op_sel:[0,1,0] op_sel_hi:[1,1,1]
	v_pk_fma_f32 v[66:67], v[4:5], v[44:45], v[66:67] op_sel:[0,1,0] op_sel_hi:[1,1,1]
	v_pk_fma_f32 v[64:65], v[6:7], v[42:43], v[64:65] op_sel_hi:[1,0,1]
	v_pk_fma_f32 v[66:67], v[6:7], v[46:47], v[66:67] op_sel_hi:[1,0,1]
	v_pk_fma_f32 v[64:65], v[8:9], v[42:43], v[64:65] op_sel:[0,1,0] op_sel_hi:[1,1,1]
	v_pk_fma_f32 v[66:67], v[8:9], v[46:47], v[66:67] op_sel:[0,1,0] op_sel_hi:[1,1,1]
	ds_read_b128 v[16:19], v10 offset:6144
	v_add_f32_dpp v78, v65, v64 quad_perm:[1,0,3,2] row_mask:0xf bank_mask:0xf bound_ctrl:1
	ds_read_b128 v[20:23], v10 offset:14336
	ds_read_b128 v[24:27], v10 offset:22528
	v_add_f32_dpp v79, v78, v78 quad_perm:[3,2,1,0] row_mask:0xf bank_mask:0xf bound_ctrl:1
	ds_read_b128 v[28:31], v10 offset:30720
	ds_read_b128 v[32:35], v10 offset:38912
	v_add_f32_dpp v80, v79, v79 row_half_mirror row_mask:0xf bank_mask:0xf bound_ctrl:1
	ds_read_b32 v36, v11 offset:44032
	ds_read_b32 v37, v12 offset:44032
	v_add_f32_dpp v76, v80, v80 row_mirror row_mask:0xf bank_mask:0xf bound_ctrl:1
	v_pk_mul_f32 v[68:69], v[60:61], v[52:53] op_sel_hi:[1,0]
	v_pk_mul_f32 v[70:71], v[60:61], v[52:53] op_sel:[0,1] op_sel_hi:[1,1]
	v_mov_b32_dpp v77, v76 quad_perm:[1,0,3,2] row_mask:0xf bank_mask:0xf bound_ctrl:1
	v_pk_mul_f32 v[72:73], v[60:61], v[54:55] op_sel_hi:[1,0]
	v_pk_mul_f32 v[74:75], v[60:61], v[54:55] op_sel:[0,1] op_sel_hi:[1,1]
	v_pk_fma_f32 v[68:69], v[2:3], v[48:49], v[68:69] op_sel_hi:[1,0,1]
	v_pk_fma_f32 v[70:71], v[4:5], v[48:49], v[70:71] op_sel:[0,1,0] op_sel_hi:[1,1,1]
	v_pk_fma_f32 v[72:73], v[6:7], v[50:51], v[72:73] op_sel_hi:[1,0,1]
	v_pk_fma_f32 v[74:75], v[8:9], v[50:51], v[74:75] op_sel:[0,1,0] op_sel_hi:[1,1,1]
	v_pk_fma_f32 v[2:3], v[56:57], v[76:77], v[68:69] op_sel_hi:[0,1,1] neg_lo:[1,0,0] neg_hi:[1,0,0]
	v_pk_fma_f32 v[4:5], v[56:57], v[76:77], v[70:71] op_sel:[1,0,0] op_sel_hi:[1,1,1] neg_lo:[1,0,0] neg_hi:[1,0,0]
	v_add_f32_dpp v81, v67, v66 quad_perm:[1,0,3,2] row_mask:0xf bank_mask:0xf bound_ctrl:1
	v_pk_fma_f32 v[6:7], v[58:59], v[76:77], v[72:73] op_sel_hi:[0,1,1] neg_lo:[1,0,0] neg_hi:[1,0,0]
	v_pk_fma_f32 v[8:9], v[58:59], v[76:77], v[74:75] op_sel:[1,0,0] op_sel_hi:[1,1,1] neg_lo:[1,0,0] neg_hi:[1,0,0]
	v_add_f32_dpp v82, v81, v81 quad_perm:[3,2,1,0] row_mask:0xf bank_mask:0xf bound_ctrl:1
	v_fma_f32 v83, v60, v96, v82
	v_fma_f32 v82, -v76, v97, v83
	ds_write_b32 v14, v82 offset:11776
	s_waitcnt lgkmcnt(1)
	v_pk_mul_f32 v[64:65], v[2:3], v[16:17] op_sel_hi:[1,0]
	v_pk_mul_f32 v[66:67], v[2:3], v[20:21] op_sel_hi:[1,0]
	v_pk_fma_f32 v[64:65], v[4:5], v[16:17], v[64:65] op_sel:[0,1,0] op_sel_hi:[1,1,1]
	v_pk_fma_f32 v[66:67], v[4:5], v[20:21], v[66:67] op_sel:[0,1,0] op_sel_hi:[1,1,1]
	v_pk_fma_f32 v[64:65], v[6:7], v[18:19], v[64:65] op_sel_hi:[1,0,1]
	v_pk_fma_f32 v[66:67], v[6:7], v[22:23], v[66:67] op_sel_hi:[1,0,1]
	v_pk_fma_f32 v[64:65], v[8:9], v[18:19], v[64:65] op_sel:[0,1,0] op_sel_hi:[1,1,1]
	v_pk_fma_f32 v[66:67], v[8:9], v[22:23], v[66:67] op_sel:[0,1,0] op_sel_hi:[1,1,1]
	ds_read_b128 v[40:43], v10 offset:6400
	v_add_f32_dpp v78, v65, v64 quad_perm:[1,0,3,2] row_mask:0xf bank_mask:0xf bound_ctrl:1
	ds_read_b128 v[44:47], v10 offset:14592
	ds_read_b128 v[48:51], v10 offset:22784
	v_add_f32_dpp v79, v78, v78 quad_perm:[3,2,1,0] row_mask:0xf bank_mask:0xf bound_ctrl:1
	ds_read_b128 v[52:55], v10 offset:30976
	ds_read_b128 v[56:59], v10 offset:39168
	v_add_f32_dpp v80, v79, v79 row_half_mirror row_mask:0xf bank_mask:0xf bound_ctrl:1
	ds_read_b32 v60, v11 offset:44160
	ds_read_b32 v61, v12 offset:44160
	v_add_f32_dpp v76, v80, v80 row_mirror row_mask:0xf bank_mask:0xf bound_ctrl:1
	ds_read_b128 v[94:97], v100 offset:208
	v_pk_mul_f32 v[68:69], v[36:37], v[28:29] op_sel_hi:[1,0]
	v_pk_mul_f32 v[70:71], v[36:37], v[28:29] op_sel:[0,1] op_sel_hi:[1,1]
	v_mov_b32_dpp v77, v76 quad_perm:[1,0,3,2] row_mask:0xf bank_mask:0xf bound_ctrl:1
	v_pk_mul_f32 v[72:73], v[36:37], v[30:31] op_sel_hi:[1,0]
	v_pk_mul_f32 v[74:75], v[36:37], v[30:31] op_sel:[0,1] op_sel_hi:[1,1]
	v_pk_fma_f32 v[68:69], v[2:3], v[24:25], v[68:69] op_sel_hi:[1,0,1]
	v_pk_fma_f32 v[70:71], v[4:5], v[24:25], v[70:71] op_sel:[0,1,0] op_sel_hi:[1,1,1]
	v_pk_fma_f32 v[72:73], v[6:7], v[26:27], v[72:73] op_sel_hi:[1,0,1]
	v_pk_fma_f32 v[74:75], v[8:9], v[26:27], v[74:75] op_sel:[0,1,0] op_sel_hi:[1,1,1]
	v_pk_fma_f32 v[2:3], v[32:33], v[76:77], v[68:69] op_sel_hi:[0,1,1] neg_lo:[1,0,0] neg_hi:[1,0,0]
	v_pk_fma_f32 v[4:5], v[32:33], v[76:77], v[70:71] op_sel:[1,0,0] op_sel_hi:[1,1,1] neg_lo:[1,0,0] neg_hi:[1,0,0]
	v_add_f32_dpp v81, v67, v66 quad_perm:[1,0,3,2] row_mask:0xf bank_mask:0xf bound_ctrl:1
	v_pk_fma_f32 v[6:7], v[34:35], v[76:77], v[72:73] op_sel_hi:[0,1,1] neg_lo:[1,0,0] neg_hi:[1,0,0]
	v_pk_fma_f32 v[8:9], v[34:35], v[76:77], v[74:75] op_sel:[1,0,0] op_sel_hi:[1,1,1] neg_lo:[1,0,0] neg_hi:[1,0,0]
	v_add_f32_dpp v82, v81, v81 quad_perm:[3,2,1,0] row_mask:0xf bank_mask:0xf bound_ctrl:1
	v_fma_f32 v83, v36, v90, v82
	v_fma_f32 v82, -v76, v91, v83
	ds_write_b32 v14, v82 offset:12288
	s_waitcnt lgkmcnt(1)
; #define LAS __attribute__((address_space(3)))
; template <int CTRL> __device__ __forceinline__ float dppf(float x) { return __builtin_bit_cast(float, __builtin_amdgcn_mov_dpp(__builtin_bit_cast(int, x), CTRL, 0xf, 0xf, true)); }
; __device__ __forceinline__ float sum16(float x) { x = sum8(x); x += dppf<0x140>(x); return x; }
; __device__ __forceinline__ void rwkv_item(LAS unsigned char* lds, int l, const bf16_t* PROJ, const bf16_t* LO, bf16_t* YR, float* BON, int b, int h, int qv) {
;     ...
;             for (int t = 0; t < CH; ++t) {
;                 const int tn = (t + 1) & (CH - 1);
;                 const LAS float* pn = pk + tn * 64;
;                 const f32x4 nkk = *(const LAS f32x4*)(pn), nwr = *(const LAS f32x4*)(pn + 2048), nw = *(const LAS f32x4*)(pn + 4096), nk = *(const LAS f32x4*)(pn + 6144), na = *(const LAS f32x4*)(pn + 8192);
;                 const float nv0 = pv[tn * 32], nv1 = pv[tn * 32 + 4]; const f32x2 nsc = *(const LAS f32x2*)(ps + 2 * tn);
;                 float sa[2], yp[2];
; #pragma unroll
;                 for (int c = 0; c < 2; ++c) { const f32x2 pa = S23[c] * kk4.hi + S01[c] * kk4.lo, pb = S23[c] * wr4.hi + S01[c] * wr4.lo; sa[c] = pa.x + pa.y; yp[c] = pb.x + pb.y; }
; #pragma unroll
;                 for (int c = 0; c < 2; ++c) { sa[c] = sum16(sa[c]); yp[c] += dppf<0xB1>(yp[c]); yp[c] += dppf<0x4E>(yp[c]); }
; #pragma unroll
;                 for (int c = 0; c < 2; ++c) {
;                     S01[c] = S01[c] * w4.lo + (k4.lo * vv[c] - a4.lo * sa[c]);
;                     S23[c] = S23[c] * w4.hi + (k4.hi * vv[c] - a4.hi * sa[c]);
;                     py[(t * 32 + 4 * c) * 4] = yp[c] + 0.25f * (vv[c] * sc.x - sa[c] * sc.y);
;                 }
;                 kk4 = nkk; wr4 = nwr; w4 = nw; k4 = nk; a4 = na; vv[0] = nv0; vv[1] = nv1; sc = nsc;
;             }
	v_pk_mul_f32 v[64:65], v[2:3], v[40:41] op_sel_hi:[1,0]
	v_pk_mul_f32 v[66:67], v[2:3], v[44:45] op_sel_hi:[1,0]
	v_pk_fma_f32 v[64:65], v[4:5], v[40:41], v[64:65] op_sel:[0,1,0] op_sel_hi:[1,1,1]
	v_pk_fma_f32 v[66:67], v[4:5], v[44:45], v[66:67] op_sel:[0,1,0] op_sel_hi:[1,1,1]
	v_pk_fma_f32 v[64:65], v[6:7], v[42:43], v[64:65] op_sel_hi:[1,0,1]
	v_pk_fma_f32 v[66:67], v[6:7], v[46:47], v[66:67] op_sel_hi:[1,0,1]
	v_pk_fma_f32 v[64:65], v[8:9], v[42:43], v[64:65] op_sel:[0,1,0] op_sel_hi:[1,1,1]
	v_pk_fma_f32 v[66:67], v[8:9], v[46:47], v[66:67] op_sel:[0,1,0] op_sel_hi:[1,1,1]
	ds_read_b128 v[16:19], v10 offset:6656
	v_add_f32_dpp v78, v65, v64 quad_perm:[1,0,3,2] row_mask:0xf bank_mask:0xf bound_ctrl:1
	ds_read_b128 v[20:23], v10 offset:14848
	ds_read_b128 v[24:27], v10 offset:23040
	v_add_f32_dpp v79, v78, v78 quad_perm:[3,2,1,0] row_mask:0xf bank_mask:0xf bound_ctrl:1
	ds_read_b128 v[28:31], v10 offset:31232
	ds_read_b128 v[32:35], v10 offset:39424
	v_add_f32_dpp v80, v79, v79 row_half_mirror row_mask:0xf bank_mask:0xf bound_ctrl:1
	ds_read_b32 v36, v11 offset:44288
	ds_read_b32 v37, v12 offset:44288
	v_add_f32_dpp v76, v80, v80 row_mirror row_mask:0xf bank_mask:0xf bound_ctrl:1
	v_pk_mul_f32 v[68:69], v[60:61], v[52:53] op_sel_hi:[1,0]
	v_pk_mul_f32 v[70:71], v[60:61], v[52:53] op_sel:[0,1] op_sel_hi:[1,1]
	v_mov_b32_dpp v77, v76 quad_perm:[1,0,3,2] row_mask:0xf bank_mask:0xf bound_ctrl:1
	v_pk_mul_f32 v[72:73], v[60:61], v[54:55] op_sel_hi:[1,0]
	v_pk_mul_f32 v[74:75], v[60:61], v[54:55] op_sel:[0,1] op_sel_hi:[1,1]
	v_pk_fma_f32 v[68:69], v[2:3], v[48:49], v[68:69] op_sel_hi:[1,0,1]
	v_pk_fma_f32 v[70:71], v[4:5], v[48:49], v[70:71] op_sel:[0,1,0] op_sel_hi:[1,1,1]
	v_pk_fma_f32 v[72:73], v[6:7], v[50:51], v[72:73] op_sel_hi:[1,0,1]
	v_pk_fma_f32 v[74:75], v[8:9], v[50:51], v[74:75] op_sel:[0,1,0] op_sel_hi:[1,1,1]
	v_pk_fma_f32 v[2:3], v[56:57], v[76:77], v[68:69] op_sel_hi:[0,1,1] neg_lo:[1,0,0] neg_hi:[1,0,0]
	v_pk_fma_f32 v[4:5], v[56:57], v[76:77], v[70:71] op_sel:[1,0,0] op_sel_hi:[1,1,1] neg_lo:[1,0,0] neg_hi:[1,0,0]
	v_add_f32_dpp v81, v67, v66 quad_perm:[1,0,3,2] row_mask:0xf bank_mask:0xf bound_ctrl:1
	v_pk_fma_f32 v[6:7], v[58:59], v[76:77], v[72:73] op_sel_hi:[0,1,1] neg_lo:[1,0,0] neg_hi:[1,0,0]
	v_pk_fma_f32 v[8:9], v[58:59], v[76:77], v[74:75] op_sel:[1,0,0] op_sel_hi:[1,1,1] neg_lo:[1,0,0] neg_hi:[1,0,0]
	v_add_f32_dpp v82, v81, v81 quad_perm:[3,2,1,0] row_mask:0xf bank_mask:0xf bound_ctrl:1
	v_fma_f32 v83, v60, v92, v82
	v_fma_f32 v82, -v76, v93, v83
	ds_write_b32 v14, v82 offset:12800
	s_waitcnt lgkmcnt(1)
	v_pk_mul_f32 v[64:65], v[2:3], v[16:17] op_sel_hi:[1,0]
	v_pk_mul_f32 v[66:67], v[2:3], v[20:21] op_sel_hi:[1,0]
	v_pk_fma_f32 v[64:65], v[4:5], v[16:17], v[64:65] op_sel:[0,1,0] op_sel_hi:[1,1,1]
	v_pk_fma_f32 v[66:67], v[4:5], v[20:21], v[66:67] op_sel:[0,1,0] op_sel_hi:[1,1,1]
	v_pk_fma_f32 v[64:65], v[6:7], v[18:19], v[64:65] op_sel_hi:[1,0,1]
	v_pk_fma_f32 v[66:67], v[6:7], v[22:23], v[66:67] op_sel_hi:[1,0,1]
	v_pk_fma_f32 v[64:65], v[8:9], v[18:19], v[64:65] op_sel:[0,1,0] op_sel_hi:[1,1,1]
	v_pk_fma_f32 v[66:67], v[8:9], v[22:23], v[66:67] op_sel:[0,1,0] op_sel_hi:[1,1,1]
	ds_read_b128 v[40:43], v10 offset:6912
	v_add_f32_dpp v78, v65, v64 quad_perm:[1,0,3,2] row_mask:0xf bank_mask:0xf bound_ctrl:1
	ds_read_b128 v[44:47], v10 offset:15104
	ds_read_b128 v[48:51], v10 offset:23296
	v_add_f32_dpp v79, v78, v78 quad_perm:[3,2,1,0] row_mask:0xf bank_mask:0xf bound_ctrl:1
	ds_read_b128 v[52:55], v10 offset:31488
	ds_read_b128 v[56:59], v10 offset:39680
	v_add_f32_dpp v80, v79, v79 row_half_mirror row_mask:0xf bank_mask:0xf bound_ctrl:1
	ds_read_b32 v60, v11 offset:44416
	ds_read_b32 v61, v12 offset:44416
	v_add_f32_dpp v76, v80, v80 row_mirror row_mask:0xf bank_mask:0xf bound_ctrl:1
	ds_read_b128 v[90:93], v100 offset:224
	v_pk_mul_f32 v[68:69], v[36:37], v[28:29] op_sel_hi:[1,0]
	v_pk_mul_f32 v[70:71], v[36:37], v[28:29] op_sel:[0,1] op_sel_hi:[1,1]
	v_mov_b32_dpp v77, v76 quad_perm:[1,0,3,2] row_mask:0xf bank_mask:0xf bound_ctrl:1
	v_pk_mul_f32 v[72:73], v[36:37], v[30:31] op_sel_hi:[1,0]
	v_pk_mul_f32 v[74:75], v[36:37], v[30:31] op_sel:[0,1] op_sel_hi:[1,1]
	v_pk_fma_f32 v[68:69], v[2:3], v[24:25], v[68:69] op_sel_hi:[1,0,1]
	v_pk_fma_f32 v[70:71], v[4:5], v[24:25], v[70:71] op_sel:[0,1,0] op_sel_hi:[1,1,1]
	v_pk_fma_f32 v[72:73], v[6:7], v[26:27], v[72:73] op_sel_hi:[1,0,1]
	v_pk_fma_f32 v[74:75], v[8:9], v[26:27], v[74:75] op_sel:[0,1,0] op_sel_hi:[1,1,1]
	v_pk_fma_f32 v[2:3], v[32:33], v[76:77], v[68:69] op_sel_hi:[0,1,1] neg_lo:[1,0,0] neg_hi:[1,0,0]
	v_pk_fma_f32 v[4:5], v[32:33], v[76:77], v[70:71] op_sel:[1,0,0] op_sel_hi:[1,1,1] neg_lo:[1,0,0] neg_hi:[1,0,0]
	v_add_f32_dpp v81, v67, v66 quad_perm:[1,0,3,2] row_mask:0xf bank_mask:0xf bound_ctrl:1
	v_pk_fma_f32 v[6:7], v[34:35], v[76:77], v[72:73] op_sel_hi:[0,1,1] neg_lo:[1,0,0] neg_hi:[1,0,0]
	v_pk_fma_f32 v[8:9], v[34:35], v[76:77], v[74:75] op_sel:[1,0,0] op_sel_hi:[1,1,1] neg_lo:[1,0,0] neg_hi:[1,0,0]
	v_add_f32_dpp v82, v81, v81 quad_perm:[3,2,1,0] row_mask:0xf bank_mask:0xf bound_ctrl:1
	v_fma_f32 v83, v36, v94, v82
	v_fma_f32 v82, -v76, v95, v83
	ds_write_b32 v14, v82 offset:13312
	s_waitcnt lgkmcnt(1)
; #define LAS __attribute__((address_space(3)))
; template <int CTRL> __device__ __forceinline__ float dppf(float x) { return __builtin_bit_cast(float, __builtin_amdgcn_mov_dpp(__builtin_bit_cast(int, x), CTRL, 0xf, 0xf, true)); }
; __device__ __forceinline__ float sum16(float x) { x = sum8(x); x += dppf<0x140>(x); return x; }
; __device__ __forceinline__ void rwkv_item(LAS unsigned char* lds, int l, const bf16_t* PROJ, const bf16_t* LO, bf16_t* YR, float* BON, int b, int h, int qv) {
;     ...
;             for (int t = 0; t < CH; ++t) {
;                 const int tn = (t + 1) & (CH - 1);
;                 const LAS float* pn = pk + tn * 64;
;                 const f32x4 nkk = *(const LAS f32x4*)(pn), nwr = *(const LAS f32x4*)(pn + 2048), nw = *(const LAS f32x4*)(pn + 4096), nk = *(const LAS f32x4*)(pn + 6144), na = *(const LAS f32x4*)(pn + 8192);
;                 const float nv0 = pv[tn * 32], nv1 = pv[tn * 32 + 4]; const f32x2 nsc = *(const LAS f32x2*)(ps + 2 * tn);
;                 float sa[2], yp[2];
; #pragma unroll
;                 for (int c = 0; c < 2; ++c) { const f32x2 pa = S23[c] * kk4.hi + S01[c] * kk4.lo, pb = S23[c] * wr4.hi + S01[c] * wr4.lo; sa[c] = pa.x + pa.y; yp[c] = pb.x + pb.y; }
; #pragma unroll
;                 for (int c = 0; c < 2; ++c) { sa[c] = sum16(sa[c]); yp[c] += dppf<0xB1>(yp[c]); yp[c] += dppf<0x4E>(yp[c]); }
; #pragma unroll
;                 for (int c = 0; c < 2; ++c) {
;                     S01[c] = S01[c] * w4.lo + (k4.lo * vv[c] - a4.lo * sa[c]);
;                     S23[c] = S23[c] * w4.hi + (k4.hi * vv[c] - a4.hi * sa[c]);
;                     py[(t * 32 + 4 * c) * 4] = yp[c] + 0.25f * (vv[c] * sc.x - sa[c] * sc.y);
;                 }
;                 kk4 = nkk; wr4 = nwr; w4 = nw; k4 = nk; a4 = na; vv[0] = nv0; vv[1] = nv1; sc = nsc;
;             }
	v_pk_mul_f32 v[64:65], v[2:3], v[40:41] op_sel_hi:[1,0]
	v_pk_mul_f32 v[66:67], v[2:3], v[44:45] op_sel_hi:[1,0]
	v_pk_fma_f32 v[64:65], v[4:5], v[40:41], v[64:65] op_sel:[0,1,0] op_sel_hi:[1,1,1]
	v_pk_fma_f32 v[66:67], v[4:5], v[44:45], v[66:67] op_sel:[0,1,0] op_sel_hi:[1,1,1]
	v_pk_fma_f32 v[64:65], v[6:7], v[42:43], v[64:65] op_sel_hi:[1,0,1]
	v_pk_fma_f32 v[66:67], v[6:7], v[46:47], v[66:67] op_sel_hi:[1,0,1]
	v_pk_fma_f32 v[64:65], v[8:9], v[42:43], v[64:65] op_sel:[0,1,0] op_sel_hi:[1,1,1]
	v_pk_fma_f32 v[66:67], v[8:9], v[46:47], v[66:67] op_sel:[0,1,0] op_sel_hi:[1,1,1]
	ds_read_b128 v[16:19], v10 offset:7168
	v_add_f32_dpp v78, v65, v64 quad_perm:[1,0,3,2] row_mask:0xf bank_mask:0xf bound_ctrl:1
	ds_read_b128 v[20:23], v10 offset:15360
	ds_read_b128 v[24:27], v10 offset:23552
	v_add_f32_dpp v79, v78, v78 quad_perm:[3,2,1,0] row_mask:0xf bank_mask:0xf bound_ctrl:1
	ds_read_b128 v[28:31], v10 offset:31744
	ds_read_b128 v[32:35], v10 offset:39936
	v_add_f32_dpp v80, v79, v79 row_half_mirror row_mask:0xf bank_mask:0xf bound_ctrl:1
	ds_read_b32 v36, v11 offset:44544
	ds_read_b32 v37, v12 offset:44544
	v_add_f32_dpp v76, v80, v80 row_mirror row_mask:0xf bank_mask:0xf bound_ctrl:1
	v_pk_mul_f32 v[68:69], v[60:61], v[52:53] op_sel_hi:[1,0]
	v_pk_mul_f32 v[70:71], v[60:61], v[52:53] op_sel:[0,1] op_sel_hi:[1,1]
	v_mov_b32_dpp v77, v76 quad_perm:[1,0,3,2] row_mask:0xf bank_mask:0xf bound_ctrl:1
	v_pk_mul_f32 v[72:73], v[60:61], v[54:55] op_sel_hi:[1,0]
	v_pk_mul_f32 v[74:75], v[60:61], v[54:55] op_sel:[0,1] op_sel_hi:[1,1]
	v_pk_fma_f32 v[68:69], v[2:3], v[48:49], v[68:69] op_sel_hi:[1,0,1]
	v_pk_fma_f32 v[70:71], v[4:5], v[48:49], v[70:71] op_sel:[0,1,0] op_sel_hi:[1,1,1]
	v_pk_fma_f32 v[72:73], v[6:7], v[50:51], v[72:73] op_sel_hi:[1,0,1]
	v_pk_fma_f32 v[74:75], v[8:9], v[50:51], v[74:75] op_sel:[0,1,0] op_sel_hi:[1,1,1]
	v_pk_fma_f32 v[2:3], v[56:57], v[76:77], v[68:69] op_sel_hi:[0,1,1] neg_lo:[1,0,0] neg_hi:[1,0,0]
	v_pk_fma_f32 v[4:5], v[56:57], v[76:77], v[70:71] op_sel:[1,0,0] op_sel_hi:[1,1,1] neg_lo:[1,0,0] neg_hi:[1,0,0]
	v_add_f32_dpp v81, v67, v66 quad_perm:[1,0,3,2] row_mask:0xf bank_mask:0xf bound_ctrl:1
	v_pk_fma_f32 v[6:7], v[58:59], v[76:77], v[72:73] op_sel_hi:[0,1,1] neg_lo:[1,0,0] neg_hi:[1,0,0]
	v_pk_fma_f32 v[8:9], v[58:59], v[76:77], v[74:75] op_sel:[1,0,0] op_sel_hi:[1,1,1] neg_lo:[1,0,0] neg_hi:[1,0,0]
	v_add_f32_dpp v82, v81, v81 quad_perm:[3,2,1,0] row_mask:0xf bank_mask:0xf bound_ctrl:1
	v_fma_f32 v83, v60, v96, v82
	v_fma_f32 v82, -v76, v97, v83
	ds_write_b32 v14, v82 offset:13824
	s_waitcnt lgkmcnt(1)
	v_pk_mul_f32 v[64:65], v[2:3], v[16:17] op_sel_hi:[1,0]
	v_pk_mul_f32 v[66:67], v[2:3], v[20:21] op_sel_hi:[1,0]
	v_pk_fma_f32 v[64:65], v[4:5], v[16:17], v[64:65] op_sel:[0,1,0] op_sel_hi:[1,1,1]
	v_pk_fma_f32 v[66:67], v[4:5], v[20:21], v[66:67] op_sel:[0,1,0] op_sel_hi:[1,1,1]
	v_pk_fma_f32 v[64:65], v[6:7], v[18:19], v[64:65] op_sel_hi:[1,0,1]
	v_pk_fma_f32 v[66:67], v[6:7], v[22:23], v[66:67] op_sel_hi:[1,0,1]
	v_pk_fma_f32 v[64:65], v[8:9], v[18:19], v[64:65] op_sel:[0,1,0] op_sel_hi:[1,1,1]
	v_pk_fma_f32 v[66:67], v[8:9], v[22:23], v[66:67] op_sel:[0,1,0] op_sel_hi:[1,1,1]
	ds_read_b128 v[40:43], v10 offset:7424
	v_add_f32_dpp v78, v65, v64 quad_perm:[1,0,3,2] row_mask:0xf bank_mask:0xf bound_ctrl:1
	ds_read_b128 v[44:47], v10 offset:15616
	ds_read_b128 v[48:51], v10 offset:23808
	v_add_f32_dpp v79, v78, v78 quad_perm:[3,2,1,0] row_mask:0xf bank_mask:0xf bound_ctrl:1
	ds_read_b128 v[52:55], v10 offset:32000
	ds_read_b128 v[56:59], v10 offset:40192
	v_add_f32_dpp v80, v79, v79 row_half_mirror row_mask:0xf bank_mask:0xf bound_ctrl:1
	ds_read_b32 v60, v11 offset:44672
	ds_read_b32 v61, v12 offset:44672
	v_add_f32_dpp v76, v80, v80 row_mirror row_mask:0xf bank_mask:0xf bound_ctrl:1
	ds_read_b128 v[94:97], v100 offset:240
	v_pk_mul_f32 v[68:69], v[36:37], v[28:29] op_sel_hi:[1,0]
	v_pk_mul_f32 v[70:71], v[36:37], v[28:29] op_sel:[0,1] op_sel_hi:[1,1]
	v_mov_b32_dpp v77, v76 quad_perm:[1,0,3,2] row_mask:0xf bank_mask:0xf bound_ctrl:1
	v_pk_mul_f32 v[72:73], v[36:37], v[30:31] op_sel_hi:[1,0]
	v_pk_mul_f32 v[74:75], v[36:37], v[30:31] op_sel:[0,1] op_sel_hi:[1,1]
	v_pk_fma_f32 v[68:69], v[2:3], v[24:25], v[68:69] op_sel_hi:[1,0,1]
	v_pk_fma_f32 v[70:71], v[4:5], v[24:25], v[70:71] op_sel:[0,1,0] op_sel_hi:[1,1,1]
	v_pk_fma_f32 v[72:73], v[6:7], v[26:27], v[72:73] op_sel_hi:[1,0,1]
	v_pk_fma_f32 v[74:75], v[8:9], v[26:27], v[74:75] op_sel:[0,1,0] op_sel_hi:[1,1,1]
	v_pk_fma_f32 v[2:3], v[32:33], v[76:77], v[68:69] op_sel_hi:[0,1,1] neg_lo:[1,0,0] neg_hi:[1,0,0]
	v_pk_fma_f32 v[4:5], v[32:33], v[76:77], v[70:71] op_sel:[1,0,0] op_sel_hi:[1,1,1] neg_lo:[1,0,0] neg_hi:[1,0,0]
	v_add_f32_dpp v81, v67, v66 quad_perm:[1,0,3,2] row_mask:0xf bank_mask:0xf bound_ctrl:1
	v_pk_fma_f32 v[6:7], v[34:35], v[76:77], v[72:73] op_sel_hi:[0,1,1] neg_lo:[1,0,0] neg_hi:[1,0,0]
	v_pk_fma_f32 v[8:9], v[34:35], v[76:77], v[74:75] op_sel:[1,0,0] op_sel_hi:[1,1,1] neg_lo:[1,0,0] neg_hi:[1,0,0]
	v_add_f32_dpp v82, v81, v81 quad_perm:[3,2,1,0] row_mask:0xf bank_mask:0xf bound_ctrl:1
	v_fma_f32 v83, v36, v90, v82
	v_fma_f32 v82, -v76, v91, v83
	ds_write_b32 v14, v82 offset:14336
	s_waitcnt lgkmcnt(1)
; #define LAS __attribute__((address_space(3)))
; template <int CTRL> __device__ __forceinline__ float dppf(float x) { return __builtin_bit_cast(float, __builtin_amdgcn_mov_dpp(__builtin_bit_cast(int, x), CTRL, 0xf, 0xf, true)); }
; __device__ __forceinline__ float sum16(float x) { x = sum8(x); x += dppf<0x140>(x); return x; }
; __device__ __forceinline__ void rwkv_item(LAS unsigned char* lds, int l, const bf16_t* PROJ, const bf16_t* LO, bf16_t* YR, float* BON, int b, int h, int qv) {
;     ...
;             for (int t = 0; t < CH; ++t) {
;                 const int tn = (t + 1) & (CH - 1);
;                 const LAS float* pn = pk + tn * 64;
;                 const f32x4 nkk = *(const LAS f32x4*)(pn), nwr = *(const LAS f32x4*)(pn + 2048), nw = *(const LAS f32x4*)(pn + 4096), nk = *(const LAS f32x4*)(pn + 6144), na = *(const LAS f32x4*)(pn + 8192);
;                 const float nv0 = pv[tn * 32], nv1 = pv[tn * 32 + 4]; const f32x2 nsc = *(const LAS f32x2*)(ps + 2 * tn);
;                 float sa[2], yp[2];
; #pragma unroll
;                 for (int c = 0; c < 2; ++c) { const f32x2 pa = S23[c] * kk4.hi + S01[c] * kk4.lo, pb = S23[c] * wr4.hi + S01[c] * wr4.lo; sa[c] = pa.x + pa.y; yp[c] = pb.x + pb.y; }
; #pragma unroll
;                 for (int c = 0; c < 2; ++c) { sa[c] = sum16(sa[c]); yp[c] += dppf<0xB1>(yp[c]); yp[c] += dppf<0x4E>(yp[c]); }
; #pragma unroll
;                 for (int c = 0; c < 2; ++c) {
;                     S01[c] = S01[c] * w4.lo + (k4.lo * vv[c] - a4.lo * sa[c]);
;                     S23[c] = S23[c] * w4.hi + (k4.hi * vv[c] - a4.hi * sa[c]);
;                     py[(t * 32 + 4 * c) * 4] = yp[c] + 0.25f * (vv[c] * sc.x - sa[c] * sc.y);
;                 }
;                 kk4 = nkk; wr4 = nwr; w4 = nw; k4 = nk; a4 = na; vv[0] = nv0; vv[1] = nv1; sc = nsc;
;             }
	v_pk_mul_f32 v[64:65], v[2:3], v[40:41] op_sel_hi:[1,0]
	v_pk_mul_f32 v[66:67], v[2:3], v[44:45] op_sel_hi:[1,0]
	v_pk_fma_f32 v[64:65], v[4:5], v[40:41], v[64:65] op_sel:[0,1,0] op_sel_hi:[1,1,1]
	v_pk_fma_f32 v[66:67], v[4:5], v[44:45], v[66:67] op_sel:[0,1,0] op_sel_hi:[1,1,1]
	v_pk_fma_f32 v[64:65], v[6:7], v[42:43], v[64:65] op_sel_hi:[1,0,1]
	v_pk_fma_f32 v[66:67], v[6:7], v[46:47], v[66:67] op_sel_hi:[1,0,1]
	v_pk_fma_f32 v[64:65], v[8:9], v[42:43], v[64:65] op_sel:[0,1,0] op_sel_hi:[1,1,1]
	v_pk_fma_f32 v[66:67], v[8:9], v[46:47], v[66:67] op_sel:[0,1,0] op_sel_hi:[1,1,1]
	ds_read_b128 v[16:19], v10 offset:7680
	v_add_f32_dpp v78, v65, v64 quad_perm:[1,0,3,2] row_mask:0xf bank_mask:0xf bound_ctrl:1
	ds_read_b128 v[20:23], v10 offset:15872
	ds_read_b128 v[24:27], v10 offset:24064
	v_add_f32_dpp v79, v78, v78 quad_perm:[3,2,1,0] row_mask:0xf bank_mask:0xf bound_ctrl:1
	ds_read_b128 v[28:31], v10 offset:32256
	ds_read_b128 v[32:35], v10 offset:40448
	v_add_f32_dpp v80, v79, v79 row_half_mirror row_mask:0xf bank_mask:0xf bound_ctrl:1
	ds_read_b32 v36, v11 offset:44800
	ds_read_b32 v37, v12 offset:44800
	v_add_f32_dpp v76, v80, v80 row_mirror row_mask:0xf bank_mask:0xf bound_ctrl:1
	v_pk_mul_f32 v[68:69], v[60:61], v[52:53] op_sel_hi:[1,0]
	v_pk_mul_f32 v[70:71], v[60:61], v[52:53] op_sel:[0,1] op_sel_hi:[1,1]
	v_mov_b32_dpp v77, v76 quad_perm:[1,0,3,2] row_mask:0xf bank_mask:0xf bound_ctrl:1
	v_pk_mul_f32 v[72:73], v[60:61], v[54:55] op_sel_hi:[1,0]
	v_pk_mul_f32 v[74:75], v[60:61], v[54:55] op_sel:[0,1] op_sel_hi:[1,1]
	v_pk_fma_f32 v[68:69], v[2:3], v[48:49], v[68:69] op_sel_hi:[1,0,1]
	v_pk_fma_f32 v[70:71], v[4:5], v[48:49], v[70:71] op_sel:[0,1,0] op_sel_hi:[1,1,1]
	v_pk_fma_f32 v[72:73], v[6:7], v[50:51], v[72:73] op_sel_hi:[1,0,1]
	v_pk_fma_f32 v[74:75], v[8:9], v[50:51], v[74:75] op_sel:[0,1,0] op_sel_hi:[1,1,1]
	v_pk_fma_f32 v[2:3], v[56:57], v[76:77], v[68:69] op_sel_hi:[0,1,1] neg_lo:[1,0,0] neg_hi:[1,0,0]
	v_pk_fma_f32 v[4:5], v[56:57], v[76:77], v[70:71] op_sel:[1,0,0] op_sel_hi:[1,1,1] neg_lo:[1,0,0] neg_hi:[1,0,0]
	v_add_f32_dpp v81, v67, v66 quad_perm:[1,0,3,2] row_mask:0xf bank_mask:0xf bound_ctrl:1
	v_pk_fma_f32 v[6:7], v[58:59], v[76:77], v[72:73] op_sel_hi:[0,1,1] neg_lo:[1,0,0] neg_hi:[1,0,0]
	v_pk_fma_f32 v[8:9], v[58:59], v[76:77], v[74:75] op_sel:[1,0,0] op_sel_hi:[1,1,1] neg_lo:[1,0,0] neg_hi:[1,0,0]
	v_add_f32_dpp v82, v81, v81 quad_perm:[3,2,1,0] row_mask:0xf bank_mask:0xf bound_ctrl:1
	v_fma_f32 v83, v60, v92, v82
	v_fma_f32 v82, -v76, v93, v83
	ds_write_b32 v14, v82 offset:14848
	s_waitcnt lgkmcnt(1)
; #define LAS __attribute__((address_space(3)))
; template <int CTRL> __device__ __forceinline__ float dppf(float x) { return __builtin_bit_cast(float, __builtin_amdgcn_mov_dpp(__builtin_bit_cast(int, x), CTRL, 0xf, 0xf, true)); }
; __device__ __forceinline__ void rwkv_item(LAS unsigned char* lds, int l, const bf16_t* PROJ, const bf16_t* LO, bf16_t* YR, float* BON, int b, int h, int qv) {
;     ...
;         for (int ci = 0; ci < NCH; ++ci) {
;             const LAS float* pk = base + (ci & 1) * BUFF + 4 * kq; const LAS float* pv = base + (ci & 1) * BUFF + 10240 + rl; const LAS float* ps = base + (ci & 1) * BUFF + 11264;
;             LAS float* py = yA + (ci & 1) * 4096 + rl * 4 + (kq >> 2);
;             f32x4 kk4 = *(const LAS f32x4*)(pk), wr4 = *(const LAS f32x4*)(pk + 2048), w4 = *(const LAS f32x4*)(pk + 4096), k4 = *(const LAS f32x4*)(pk + 6144), a4 = *(const LAS f32x4*)(pk + 8192);
;             float vv[2] = {pv[0], pv[4]}; f32x2 sc = *(const LAS f32x2*)(ps);
; #pragma unroll 32
;             for (int t = 0; t < CH; ++t) {
;                 const int tn = (t + 1) & (CH - 1);
;                 const LAS float* pn = pk + tn * 64;
;                 const f32x4 nkk = *(const LAS f32x4*)(pn), nwr = *(const LAS f32x4*)(pn + 2048), nw = *(const LAS f32x4*)(pn + 4096), nk = *(const LAS f32x4*)(pn + 6144), na = *(const LAS f32x4*)(pn + 8192);
;                 const float nv0 = pv[tn * 32], nv1 = pv[tn * 32 + 4]; const f32x2 nsc = *(const LAS f32x2*)(ps + 2 * tn);
;                 float sa[2], yp[2];
; #pragma unroll
;                 for (int c = 0; c < 2; ++c) { const f32x2 pa = S23[c] * kk4.hi + S01[c] * kk4.lo, pb = S23[c] * wr4.hi + S01[c] * wr4.lo; sa[c] = pa.x + pa.y; yp[c] = pb.x + pb.y; }
; #pragma unroll
;                 for (int c = 0; c < 2; ++c) { sa[c] = sum16(sa[c]); yp[c] += dppf<0xB1>(yp[c]); yp[c] += dppf<0x4E>(yp[c]); }
; #pragma unroll
;                 for (int c = 0; c < 2; ++c) {
;                     S01[c] = S01[c] * w4.lo + (k4.lo * vv[c] - a4.lo * sa[c]);
;                     S23[c] = S23[c] * w4.hi + (k4.hi * vv[c] - a4.hi * sa[c]);
;                     py[(t * 32 + 4 * c) * 4] = yp[c] + 0.25f * (vv[c] * sc.x - sa[c] * sc.y);
;                 }
;                 kk4 = nkk; wr4 = nwr; w4 = nw; k4 = nk; a4 = na; vv[0] = nv0; vv[1] = nv1; sc = nsc;
;             }
;             __syncthreads();
;         }
	v_pk_mul_f32 v[64:65], v[2:3], v[16:17] op_sel_hi:[1,0]
	v_pk_mul_f32 v[66:67], v[2:3], v[20:21] op_sel_hi:[1,0]
	v_pk_fma_f32 v[64:65], v[4:5], v[16:17], v[64:65] op_sel:[0,1,0] op_sel_hi:[1,1,1]
	v_pk_fma_f32 v[66:67], v[4:5], v[20:21], v[66:67] op_sel:[0,1,0] op_sel_hi:[1,1,1]
	v_pk_fma_f32 v[64:65], v[6:7], v[18:19], v[64:65] op_sel_hi:[1,0,1]
	v_pk_fma_f32 v[66:67], v[6:7], v[22:23], v[66:67] op_sel_hi:[1,0,1]
	v_pk_fma_f32 v[64:65], v[8:9], v[18:19], v[64:65] op_sel:[0,1,0] op_sel_hi:[1,1,1]
	v_pk_fma_f32 v[66:67], v[8:9], v[22:23], v[66:67] op_sel:[0,1,0] op_sel_hi:[1,1,1]
	ds_read_b128 v[40:43], v10 offset:7936
	v_add_f32_dpp v78, v65, v64 quad_perm:[1,0,3,2] row_mask:0xf bank_mask:0xf bound_ctrl:1
	ds_read_b128 v[44:47], v10 offset:16128
	ds_read_b128 v[48:51], v10 offset:24320
	v_add_f32_dpp v79, v78, v78 quad_perm:[3,2,1,0] row_mask:0xf bank_mask:0xf bound_ctrl:1
	ds_read_b128 v[52:55], v10 offset:32512
	ds_read_b128 v[56:59], v10 offset:40704
	v_add_f32_dpp v80, v79, v79 row_half_mirror row_mask:0xf bank_mask:0xf bound_ctrl:1
	ds_read_b32 v60, v11 offset:44928
	ds_read_b32 v61, v12 offset:44928
	v_add_f32_dpp v76, v80, v80 row_mirror row_mask:0xf bank_mask:0xf bound_ctrl:1
	v_pk_mul_f32 v[68:69], v[36:37], v[28:29] op_sel_hi:[1,0]
	v_pk_mul_f32 v[70:71], v[36:37], v[28:29] op_sel:[0,1] op_sel_hi:[1,1]
	v_mov_b32_dpp v77, v76 quad_perm:[1,0,3,2] row_mask:0xf bank_mask:0xf bound_ctrl:1
	v_pk_mul_f32 v[72:73], v[36:37], v[30:31] op_sel_hi:[1,0]
	v_pk_mul_f32 v[74:75], v[36:37], v[30:31] op_sel:[0,1] op_sel_hi:[1,1]
	v_pk_fma_f32 v[68:69], v[2:3], v[24:25], v[68:69] op_sel_hi:[1,0,1]
	v_pk_fma_f32 v[70:71], v[4:5], v[24:25], v[70:71] op_sel:[0,1,0] op_sel_hi:[1,1,1]
	v_pk_fma_f32 v[72:73], v[6:7], v[26:27], v[72:73] op_sel_hi:[1,0,1]
	v_pk_fma_f32 v[74:75], v[8:9], v[26:27], v[74:75] op_sel:[0,1,0] op_sel_hi:[1,1,1]
	v_pk_fma_f32 v[2:3], v[32:33], v[76:77], v[68:69] op_sel_hi:[0,1,1] neg_lo:[1,0,0] neg_hi:[1,0,0]
	v_pk_fma_f32 v[4:5], v[32:33], v[76:77], v[70:71] op_sel:[1,0,0] op_sel_hi:[1,1,1] neg_lo:[1,0,0] neg_hi:[1,0,0]
	v_add_f32_dpp v81, v67, v66 quad_perm:[1,0,3,2] row_mask:0xf bank_mask:0xf bound_ctrl:1
	v_pk_fma_f32 v[6:7], v[34:35], v[76:77], v[72:73] op_sel_hi:[0,1,1] neg_lo:[1,0,0] neg_hi:[1,0,0]
	v_pk_fma_f32 v[8:9], v[34:35], v[76:77], v[74:75] op_sel:[1,0,0] op_sel_hi:[1,1,1] neg_lo:[1,0,0] neg_hi:[1,0,0]
	v_add_f32_dpp v82, v81, v81 quad_perm:[3,2,1,0] row_mask:0xf bank_mask:0xf bound_ctrl:1
	v_fma_f32 v83, v36, v94, v82
	v_fma_f32 v82, -v76, v95, v83
	ds_write_b32 v14, v82 offset:15360
	s_waitcnt lgkmcnt(1)
	v_pk_mul_f32 v[64:65], v[2:3], v[40:41] op_sel_hi:[1,0]
	v_pk_mul_f32 v[66:67], v[2:3], v[44:45] op_sel_hi:[1,0]
	v_pk_fma_f32 v[64:65], v[4:5], v[40:41], v[64:65] op_sel:[0,1,0] op_sel_hi:[1,1,1]
	v_pk_fma_f32 v[66:67], v[4:5], v[44:45], v[66:67] op_sel:[0,1,0] op_sel_hi:[1,1,1]
	v_pk_fma_f32 v[64:65], v[6:7], v[42:43], v[64:65] op_sel_hi:[1,0,1]
	v_pk_fma_f32 v[66:67], v[6:7], v[46:47], v[66:67] op_sel_hi:[1,0,1]
	v_pk_fma_f32 v[64:65], v[8:9], v[42:43], v[64:65] op_sel:[0,1,0] op_sel_hi:[1,1,1]
	v_pk_fma_f32 v[66:67], v[8:9], v[46:47], v[66:67] op_sel:[0,1,0] op_sel_hi:[1,1,1]
	s_nop 0
	v_add_f32_dpp v78, v65, v64 quad_perm:[1,0,3,2] row_mask:0xf bank_mask:0xf bound_ctrl:1
	s_nop 0
	s_nop 0
	v_add_f32_dpp v79, v78, v78 quad_perm:[3,2,1,0] row_mask:0xf bank_mask:0xf bound_ctrl:1
	s_nop 0
	s_nop 0
	v_add_f32_dpp v80, v79, v79 row_half_mirror row_mask:0xf bank_mask:0xf bound_ctrl:1
	s_nop 0
	s_nop 0
	v_add_f32_dpp v76, v80, v80 row_mirror row_mask:0xf bank_mask:0xf bound_ctrl:1
	v_pk_mul_f32 v[68:69], v[60:61], v[52:53] op_sel_hi:[1,0]
	v_pk_mul_f32 v[70:71], v[60:61], v[52:53] op_sel:[0,1] op_sel_hi:[1,1]
	v_mov_b32_dpp v77, v76 quad_perm:[1,0,3,2] row_mask:0xf bank_mask:0xf bound_ctrl:1
	v_pk_mul_f32 v[72:73], v[60:61], v[54:55] op_sel_hi:[1,0]
	v_pk_mul_f32 v[74:75], v[60:61], v[54:55] op_sel:[0,1] op_sel_hi:[1,1]
	v_pk_fma_f32 v[68:69], v[2:3], v[48:49], v[68:69] op_sel_hi:[1,0,1]
	v_pk_fma_f32 v[70:71], v[4:5], v[48:49], v[70:71] op_sel:[0,1,0] op_sel_hi:[1,1,1]
	v_pk_fma_f32 v[72:73], v[6:7], v[50:51], v[72:73] op_sel_hi:[1,0,1]
	v_pk_fma_f32 v[74:75], v[8:9], v[50:51], v[74:75] op_sel:[0,1,0] op_sel_hi:[1,1,1]
	v_pk_fma_f32 v[2:3], v[56:57], v[76:77], v[68:69] op_sel_hi:[0,1,1] neg_lo:[1,0,0] neg_hi:[1,0,0]
	v_pk_fma_f32 v[4:5], v[56:57], v[76:77], v[70:71] op_sel:[1,0,0] op_sel_hi:[1,1,1] neg_lo:[1,0,0] neg_hi:[1,0,0]
	v_add_f32_dpp v81, v67, v66 quad_perm:[1,0,3,2] row_mask:0xf bank_mask:0xf bound_ctrl:1
	v_pk_fma_f32 v[6:7], v[58:59], v[76:77], v[72:73] op_sel_hi:[0,1,1] neg_lo:[1,0,0] neg_hi:[1,0,0]
	v_pk_fma_f32 v[8:9], v[58:59], v[76:77], v[74:75] op_sel:[1,0,0] op_sel_hi:[1,1,1] neg_lo:[1,0,0] neg_hi:[1,0,0]
	v_add_f32_dpp v82, v81, v81 quad_perm:[3,2,1,0] row_mask:0xf bank_mask:0xf bound_ctrl:1
	v_fma_f32 v83, v60, v96, v82
	v_fma_f32 v82, -v76, v97, v83
	ds_write_b32 v14, v82 offset:15872
	s_add_i32 s30, s30, 1
	s_cmpk_eq_i32 s30, 0x80
	s_waitcnt lgkmcnt(0)
	s_barrier
	s_cbranch_scc0 .Lscan_chunk
	s_setprio 0
	s_mov_b64 s[30:31], 0
